# weight conversion item loops: all 32 loads of an item in flight before the LDS writes (P0: 7 loops unrolled x2; P11: 2 loops restructured from 2-at-a-time)
# speedup vs baseline: 1.0151x; 1.0121x over previous
; #define LAS __attribute__((address_space(3)))
; __device__ __forceinline__ void tr_item(const float* W, int N, bf16* WT, int ldk, int k0, int scol0, int drow0, LAS float* scr, int lane) {
;     if (scol0 >= 0) {
; #pragma unroll 8
;         for (int i = 0; i < 32; ++i) { const int kk = 2 * i + (lane >> 5); scr[kk * 33 + (lane & 31)] = W[(size_t)(k0 + kk) * N + scol0 + (lane & 31)]; }
;     } else {
; #pragma unroll 8
;         for (int i = 0; i < 32; ++i) { const int kk = 2 * i + (lane >> 5); scr[kk * 33 + (lane & 31)] = 0.f; }
;     }
;     asm volatile("s_waitcnt vmcnt(0) lgkmcnt(0)" ::: "memory");
.LBB0_106:
	s_lshl_b32 s19, s4, 1
	s_lshl_b32 s22, s3, 1
	v_add_u32_e32 v46, s19, v30
	v_add_u32_e32 v48, s22, v17
	v_add_u32_e32 v52, s22, v19
	v_add_u32_e32 v50, s19, v32
	v_add_u32_e32 v56, s22, v21
	v_add_u32_e32 v54, s19, v34
	v_add_u32_e32 v60, s22, v23
	v_add_u32_e32 v58, s19, v36
	v_add_u32_e32 v64, s22, v31
	v_add_u32_e32 v62, s19, v38
	v_add_u32_e32 v68, s22, v33
	v_add_u32_e32 v66, s19, v40
	v_add_u32_e32 v72, s22, v35
	v_add_u32_e32 v70, s19, v42
	v_add_u32_e32 v76, s22, v37
	v_add_u32_e32 v74, s19, v44
	v_mad_i64_i32 v[46:47], s[20:21], v46, s69, v[28:29]
	v_mad_i64_i32 v[48:49], s[20:21], v48, s69, v[28:29]
	v_mad_i64_i32 v[50:51], s[20:21], v50, s69, v[28:29]
	v_mad_i64_i32 v[52:53], s[20:21], v52, s69, v[28:29]
	v_mad_i64_i32 v[54:55], s[20:21], v54, s69, v[28:29]
	v_mad_i64_i32 v[56:57], s[20:21], v56, s69, v[28:29]
	v_mad_i64_i32 v[58:59], s[20:21], v58, s69, v[28:29]
	v_mad_i64_i32 v[60:61], s[20:21], v60, s69, v[28:29]
	v_mad_i64_i32 v[62:63], s[20:21], v62, s69, v[28:29]
	v_mad_i64_i32 v[64:65], s[20:21], v64, s69, v[28:29]
	v_mad_i64_i32 v[66:67], s[20:21], v66, s69, v[28:29]
	v_mad_i64_i32 v[68:69], s[20:21], v68, s69, v[28:29]
	v_mad_i64_i32 v[70:71], s[20:21], v70, s69, v[28:29]
	v_mad_i64_i32 v[72:73], s[20:21], v72, s69, v[28:29]
	v_mad_i64_i32 v[74:75], s[20:21], v74, s69, v[28:29]
	v_mad_i64_i32 v[76:77], s[20:21], v76, s69, v[28:29]
	global_load_dword v78, v[46:47], off
	global_load_dword v79, v[48:49], off
	global_load_dword v80, v[50:51], off
	global_load_dword v81, v[52:53], off
	global_load_dword v82, v[54:55], off
	global_load_dword v83, v[56:57], off
	global_load_dword v84, v[58:59], off
	global_load_dword v85, v[60:61], off
	global_load_dword v86, v[62:63], off
	global_load_dword v87, v[64:65], off
	global_load_dword v88, v[66:67], off
	global_load_dword v89, v[68:69], off
	global_load_dword v90, v[70:71], off
	global_load_dword v91, v[72:73], off
	global_load_dword v92, v[74:75], off
	global_load_dword v93, v[76:77], off
	s_add_i32 s4, s4, 16
	s_add_i32 s3, s3, 16
	s_add_i32 s5, s5, -16
	v_add_u32_e32 v46, s19, v4
	v_add_u32_e32 v48, s22, v1
	v_add_u32_e32 v52, s22, v3
	v_add_u32_e32 v50, s19, v6
	v_add_u32_e32 v56, s22, v5
	v_add_u32_e32 v54, s19, v8
	v_add_u32_e32 v60, s22, v7
	v_add_u32_e32 v58, s19, v10
	v_add_u32_e32 v64, s22, v9
	v_add_u32_e32 v62, s19, v12
	v_add_u32_e32 v68, s22, v11
	v_add_u32_e32 v66, s19, v14
	v_add_u32_e32 v72, s22, v13
	v_add_u32_e32 v70, s19, v16
	v_add_u32_e32 v76, s22, v15
	v_add_u32_e32 v74, s19, v18
	s_cmp_eq_u32 s5, 0
	v_mad_u64_u32 v[46:47], s[20:21], v46, s57, v[22:23]
	v_mad_u64_u32 v[48:49], s[20:21], v48, s57, v[22:23]
	v_mad_u64_u32 v[50:51], s[20:21], v50, s57, v[22:23]
	v_mad_u64_u32 v[52:53], s[20:21], v52, s57, v[22:23]
	v_mad_u64_u32 v[54:55], s[20:21], v54, s57, v[22:23]
	v_mad_u64_u32 v[56:57], s[20:21], v56, s57, v[22:23]
	v_mad_u64_u32 v[58:59], s[20:21], v58, s57, v[22:23]
	v_mad_u64_u32 v[60:61], s[20:21], v60, s57, v[22:23]
	v_mad_u64_u32 v[62:63], s[20:21], v62, s57, v[22:23]
	v_mad_u64_u32 v[64:65], s[20:21], v64, s57, v[22:23]
	v_mad_u64_u32 v[66:67], s[20:21], v66, s57, v[22:23]
	v_mad_u64_u32 v[68:69], s[20:21], v68, s57, v[22:23]
	v_mad_u64_u32 v[70:71], s[20:21], v70, s57, v[22:23]
	v_mad_u64_u32 v[72:73], s[20:21], v72, s57, v[22:23]
	v_mad_u64_u32 v[74:75], s[20:21], v74, s57, v[22:23]
	v_mad_u64_u32 v[76:77], s[20:21], v76, s57, v[22:23]
	s_lshl_b32 s19, s4, 1
	s_lshl_b32 s22, s3, 1
	v_add_u32_e32 v112, s19, v30
	v_add_u32_e32 v114, s22, v17
	v_add_u32_e32 v118, s22, v19
	v_add_u32_e32 v116, s19, v32
	v_add_u32_e32 v122, s22, v21
	v_add_u32_e32 v120, s19, v34
	v_add_u32_e32 v126, s22, v23
	v_add_u32_e32 v124, s19, v36
	v_add_u32_e32 v130, s22, v31
	v_add_u32_e32 v128, s19, v38
	v_add_u32_e32 v134, s22, v33
	v_add_u32_e32 v132, s19, v40
	v_add_u32_e32 v138, s22, v35
	v_add_u32_e32 v136, s19, v42
	v_add_u32_e32 v142, s22, v37
	v_add_u32_e32 v140, s19, v44
	v_mad_i64_i32 v[112:113], s[20:21], v112, s69, v[28:29]
	v_mad_i64_i32 v[114:115], s[20:21], v114, s69, v[28:29]
	v_mad_i64_i32 v[116:117], s[20:21], v116, s69, v[28:29]
	v_mad_i64_i32 v[118:119], s[20:21], v118, s69, v[28:29]
	v_mad_i64_i32 v[120:121], s[20:21], v120, s69, v[28:29]
	v_mad_i64_i32 v[122:123], s[20:21], v122, s69, v[28:29]
	v_mad_i64_i32 v[124:125], s[20:21], v124, s69, v[28:29]
	v_mad_i64_i32 v[126:127], s[20:21], v126, s69, v[28:29]
	v_mad_i64_i32 v[128:129], s[20:21], v128, s69, v[28:29]
	v_mad_i64_i32 v[130:131], s[20:21], v130, s69, v[28:29]
	v_mad_i64_i32 v[132:133], s[20:21], v132, s69, v[28:29]
	v_mad_i64_i32 v[134:135], s[20:21], v134, s69, v[28:29]
	v_mad_i64_i32 v[136:137], s[20:21], v136, s69, v[28:29]
	v_mad_i64_i32 v[138:139], s[20:21], v138, s69, v[28:29]
	v_mad_i64_i32 v[140:141], s[20:21], v140, s69, v[28:29]
	v_mad_i64_i32 v[142:143], s[20:21], v142, s69, v[28:29]
	global_load_dword v144, v[112:113], off
	global_load_dword v145, v[114:115], off
	global_load_dword v146, v[116:117], off
	global_load_dword v147, v[118:119], off
	global_load_dword v148, v[120:121], off
	global_load_dword v149, v[122:123], off
	global_load_dword v150, v[124:125], off
	global_load_dword v151, v[126:127], off
	global_load_dword v152, v[128:129], off
	global_load_dword v153, v[130:131], off
	global_load_dword v154, v[132:133], off
	global_load_dword v155, v[134:135], off
	global_load_dword v156, v[136:137], off
	global_load_dword v157, v[138:139], off
	global_load_dword v158, v[140:141], off
	global_load_dword v159, v[142:143], off
	s_add_i32 s4, s4, 16
	s_add_i32 s3, s3, 16
	s_add_i32 s5, s5, -16
	v_add_u32_e32 v112, s19, v4
	v_add_u32_e32 v114, s22, v1
	v_add_u32_e32 v118, s22, v3
	v_add_u32_e32 v116, s19, v6
	v_add_u32_e32 v122, s22, v5
	v_add_u32_e32 v120, s19, v8
	v_add_u32_e32 v126, s22, v7
	v_add_u32_e32 v124, s19, v10
	v_add_u32_e32 v130, s22, v9
	v_add_u32_e32 v128, s19, v12
	v_add_u32_e32 v134, s22, v11
	v_add_u32_e32 v132, s19, v14
	v_add_u32_e32 v138, s22, v13
	v_add_u32_e32 v136, s19, v16
	v_add_u32_e32 v142, s22, v15
	v_add_u32_e32 v140, s19, v18
	s_cmp_eq_u32 s5, 0
	v_mad_u64_u32 v[112:113], s[20:21], v112, s57, v[22:23]
	v_mad_u64_u32 v[114:115], s[20:21], v114, s57, v[22:23]
	v_mad_u64_u32 v[116:117], s[20:21], v116, s57, v[22:23]
	v_mad_u64_u32 v[118:119], s[20:21], v118, s57, v[22:23]
	v_mad_u64_u32 v[120:121], s[20:21], v120, s57, v[22:23]
	v_mad_u64_u32 v[122:123], s[20:21], v122, s57, v[22:23]
	v_mad_u64_u32 v[124:125], s[20:21], v124, s57, v[22:23]
	v_mad_u64_u32 v[126:127], s[20:21], v126, s57, v[22:23]
	v_mad_u64_u32 v[128:129], s[20:21], v128, s57, v[22:23]
	v_mad_u64_u32 v[130:131], s[20:21], v130, s57, v[22:23]
	v_mad_u64_u32 v[132:133], s[20:21], v132, s57, v[22:23]
	v_mad_u64_u32 v[134:135], s[20:21], v134, s57, v[22:23]
	v_mad_u64_u32 v[136:137], s[20:21], v136, s57, v[22:23]
	v_mad_u64_u32 v[138:139], s[20:21], v138, s57, v[22:23]
	v_mad_u64_u32 v[140:141], s[20:21], v140, s57, v[22:23]
	v_mad_u64_u32 v[142:143], s[20:21], v142, s57, v[22:23]
	s_waitcnt vmcnt(16)
; __device__ __forceinline__ void tr_item(const float* W, int N, bf16* WT, int ldk, int k0, int scol0, int drow0, LAS float* scr, int lane) {
;     ...
;         for (int i = 0; i < 32; ++i) { const int kk = 2 * i + (lane >> 5); scr[kk * 33 + (lane & 31)] = W[(size_t)(k0 + kk) * N + scol0 + (lane & 31)]; }
;     } else {
; #pragma unroll 8
;         for (int i = 0; i < 32; ++i) { const int kk = 2 * i + (lane >> 5); scr[kk * 33 + (lane & 31)] = 0.f; }
;     }
;     asm volatile("s_waitcnt vmcnt(0) lgkmcnt(0)" ::: "memory");
	ds_write_b32 v46, v78
	ds_write_b32 v48, v79
	ds_write_b32 v50, v80
	ds_write_b32 v52, v81
	ds_write_b32 v54, v82
	ds_write_b32 v56, v83
	ds_write_b32 v58, v84
	ds_write_b32 v60, v85
	ds_write_b32 v62, v86
	ds_write_b32 v64, v87
	ds_write_b32 v66, v88
	ds_write_b32 v68, v89
	ds_write_b32 v70, v90
	ds_write_b32 v72, v91
	ds_write_b32 v74, v92
	ds_write_b32 v76, v93
	s_waitcnt vmcnt(0)
	ds_write_b32 v112, v144
	ds_write_b32 v114, v145
	ds_write_b32 v116, v146
	ds_write_b32 v118, v147
	ds_write_b32 v120, v148
	ds_write_b32 v122, v149
	ds_write_b32 v124, v150
	ds_write_b32 v126, v151
	ds_write_b32 v128, v152
	ds_write_b32 v130, v153
	ds_write_b32 v132, v154
	ds_write_b32 v134, v155
	ds_write_b32 v136, v156
	ds_write_b32 v138, v157
	ds_write_b32 v140, v158
	ds_write_b32 v142, v159
	s_branch .LBB0_99

; #define LAS __attribute__((address_space(3)))
; __device__ __forceinline__ void tr_item(const float* W, int N, bf16* WT, int ldk, int k0, int scol0, int drow0, LAS float* scr, int lane) {
;     if (scol0 >= 0) {
; #pragma unroll 8
;         for (int i = 0; i < 32; ++i) { const int kk = 2 * i + (lane >> 5); scr[kk * 33 + (lane & 31)] = W[(size_t)(k0 + kk) * N + scol0 + (lane & 31)]; }
;     } else {
; #pragma unroll 8
;         for (int i = 0; i < 32; ++i) { const int kk = 2 * i + (lane >> 5); scr[kk * 33 + (lane & 31)] = 0.f; }
;     }
;     asm volatile("s_waitcnt vmcnt(0) lgkmcnt(0)" ::: "memory");
.LBB0_116:
	s_lshl_b32 s17, s4, 1
	s_lshl_b32 s19, s3, 1
	v_add_u32_e32 v48, s17, v30
	v_add_u32_e32 v46, s19, v17
	v_add_u32_e32 v50, s19, v19
	v_add_u32_e32 v52, s17, v32
	v_add_u32_e32 v54, s19, v21
	v_add_u32_e32 v56, s17, v34
	v_add_u32_e32 v58, s19, v23
	v_add_u32_e32 v60, s17, v36
	v_add_u32_e32 v62, s19, v31
	v_add_u32_e32 v64, s17, v38
	v_add_u32_e32 v66, s19, v33
	v_add_u32_e32 v68, s17, v40
	v_add_u32_e32 v70, s19, v35
	v_add_u32_e32 v72, s17, v42
	v_add_u32_e32 v74, s19, v37
	v_add_u32_e32 v76, s17, v44
	v_ashrrev_i32_e32 v49, 31, v48
	v_ashrrev_i32_e32 v47, 31, v46
	v_ashrrev_i32_e32 v53, 31, v52
	v_ashrrev_i32_e32 v51, 31, v50
	v_ashrrev_i32_e32 v57, 31, v56
	v_ashrrev_i32_e32 v55, 31, v54
	v_ashrrev_i32_e32 v61, 31, v60
	v_ashrrev_i32_e32 v59, 31, v58
	v_ashrrev_i32_e32 v65, 31, v64
	v_ashrrev_i32_e32 v63, 31, v62
	v_ashrrev_i32_e32 v69, 31, v68
	v_ashrrev_i32_e32 v67, 31, v66
	v_ashrrev_i32_e32 v73, 31, v72
	v_ashrrev_i32_e32 v71, 31, v70
	v_ashrrev_i32_e32 v77, 31, v76
	v_ashrrev_i32_e32 v75, 31, v74
	v_lshlrev_b64 v[48:49], 13, v[48:49]
	v_lshlrev_b64 v[46:47], 13, v[46:47]
	v_lshlrev_b64 v[50:51], 13, v[50:51]
	v_lshlrev_b64 v[52:53], 13, v[52:53]
	v_lshlrev_b64 v[54:55], 13, v[54:55]
	v_lshlrev_b64 v[56:57], 13, v[56:57]
	v_lshlrev_b64 v[58:59], 13, v[58:59]
	v_lshlrev_b64 v[60:61], 13, v[60:61]
	v_lshlrev_b64 v[62:63], 13, v[62:63]
	v_lshlrev_b64 v[64:65], 13, v[64:65]
	v_lshlrev_b64 v[66:67], 13, v[66:67]
	v_lshlrev_b64 v[68:69], 13, v[68:69]
	v_lshlrev_b64 v[70:71], 13, v[70:71]
	v_lshlrev_b64 v[72:73], 13, v[72:73]
	v_lshlrev_b64 v[74:75], 13, v[74:75]
	v_lshlrev_b64 v[76:77], 13, v[76:77]
	v_lshl_add_u64 v[48:49], v[28:29], 0, v[48:49]
	v_lshl_add_u64 v[46:47], v[28:29], 0, v[46:47]
	v_lshl_add_u64 v[52:53], v[28:29], 0, v[52:53]
	v_lshl_add_u64 v[50:51], v[28:29], 0, v[50:51]
	v_lshl_add_u64 v[56:57], v[28:29], 0, v[56:57]
	v_lshl_add_u64 v[54:55], v[28:29], 0, v[54:55]
	v_lshl_add_u64 v[60:61], v[28:29], 0, v[60:61]
	v_lshl_add_u64 v[58:59], v[28:29], 0, v[58:59]
	v_lshl_add_u64 v[64:65], v[28:29], 0, v[64:65]
	v_lshl_add_u64 v[62:63], v[28:29], 0, v[62:63]
	v_lshl_add_u64 v[68:69], v[28:29], 0, v[68:69]
	v_lshl_add_u64 v[66:67], v[28:29], 0, v[66:67]
	v_lshl_add_u64 v[72:73], v[28:29], 0, v[72:73]
	v_lshl_add_u64 v[70:71], v[28:29], 0, v[70:71]
	v_lshl_add_u64 v[76:77], v[28:29], 0, v[76:77]
	v_lshl_add_u64 v[74:75], v[28:29], 0, v[74:75]
	global_load_dword v78, v[48:49], off
	global_load_dword v79, v[46:47], off
	global_load_dword v80, v[52:53], off
	global_load_dword v81, v[50:51], off
	global_load_dword v82, v[56:57], off
	global_load_dword v83, v[54:55], off
	global_load_dword v84, v[60:61], off
	global_load_dword v85, v[58:59], off
	global_load_dword v86, v[64:65], off
	global_load_dword v87, v[62:63], off
	global_load_dword v88, v[68:69], off
	global_load_dword v89, v[66:67], off
	global_load_dword v90, v[72:73], off
	global_load_dword v91, v[70:71], off
	global_load_dword v92, v[76:77], off
	global_load_dword v93, v[74:75], off
	s_add_i32 s4, s4, 16
	s_add_i32 s3, s3, 16
	s_add_i32 s5, s5, -16
	v_add_u32_e32 v46, s17, v4
	v_add_u32_e32 v48, s19, v1
	v_add_u32_e32 v52, s19, v3
	v_add_u32_e32 v50, s17, v6
	v_add_u32_e32 v56, s19, v5
	v_add_u32_e32 v54, s17, v8
	v_add_u32_e32 v60, s19, v7
	v_add_u32_e32 v58, s17, v10
	v_add_u32_e32 v64, s19, v9
	v_add_u32_e32 v62, s17, v12
	v_add_u32_e32 v68, s19, v11
	v_add_u32_e32 v66, s17, v14
	v_add_u32_e32 v72, s19, v13
	v_add_u32_e32 v70, s17, v16
	v_add_u32_e32 v76, s19, v15
	v_add_u32_e32 v74, s17, v18
	s_cmp_eq_u32 s5, 0
	v_mad_u64_u32 v[46:47], s[20:21], v46, s57, v[22:23]
	v_mad_u64_u32 v[48:49], s[20:21], v48, s57, v[22:23]
	v_mad_u64_u32 v[50:51], s[20:21], v50, s57, v[22:23]
	v_mad_u64_u32 v[52:53], s[20:21], v52, s57, v[22:23]
	v_mad_u64_u32 v[54:55], s[20:21], v54, s57, v[22:23]
	v_mad_u64_u32 v[56:57], s[20:21], v56, s57, v[22:23]
	v_mad_u64_u32 v[58:59], s[20:21], v58, s57, v[22:23]
	v_mad_u64_u32 v[60:61], s[20:21], v60, s57, v[22:23]
	v_mad_u64_u32 v[62:63], s[20:21], v62, s57, v[22:23]
	v_mad_u64_u32 v[64:65], s[20:21], v64, s57, v[22:23]
	v_mad_u64_u32 v[66:67], s[20:21], v66, s57, v[22:23]
	v_mad_u64_u32 v[68:69], s[20:21], v68, s57, v[22:23]
	v_mad_u64_u32 v[70:71], s[20:21], v70, s57, v[22:23]
	v_mad_u64_u32 v[72:73], s[20:21], v72, s57, v[22:23]
	v_mad_u64_u32 v[74:75], s[20:21], v74, s57, v[22:23]
	v_mad_u64_u32 v[76:77], s[20:21], v76, s57, v[22:23]
	s_lshl_b32 s17, s4, 1
	s_lshl_b32 s19, s3, 1
	v_add_u32_e32 v114, s17, v30
	v_add_u32_e32 v112, s19, v17
	v_add_u32_e32 v116, s19, v19
	v_add_u32_e32 v118, s17, v32
	v_add_u32_e32 v120, s19, v21
	v_add_u32_e32 v122, s17, v34
	v_add_u32_e32 v124, s19, v23
	v_add_u32_e32 v126, s17, v36
	v_add_u32_e32 v128, s19, v31
	v_add_u32_e32 v130, s17, v38
	v_add_u32_e32 v132, s19, v33
	v_add_u32_e32 v134, s17, v40
	v_add_u32_e32 v136, s19, v35
	v_add_u32_e32 v138, s17, v42
	v_add_u32_e32 v140, s19, v37
	v_add_u32_e32 v142, s17, v44
	v_ashrrev_i32_e32 v115, 31, v114
; #define LAS __attribute__((address_space(3)))
; __device__ __forceinline__ void tr_item(const float* W, int N, bf16* WT, int ldk, int k0, int scol0, int drow0, LAS float* scr, int lane) {
;     if (scol0 >= 0) {
; #pragma unroll 8
;         for (int i = 0; i < 32; ++i) { const int kk = 2 * i + (lane >> 5); scr[kk * 33 + (lane & 31)] = W[(size_t)(k0 + kk) * N + scol0 + (lane & 31)]; }
;     } else {
; #pragma unroll 8
;         for (int i = 0; i < 32; ++i) { const int kk = 2 * i + (lane >> 5); scr[kk * 33 + (lane & 31)] = 0.f; }
;     }
;     asm volatile("s_waitcnt vmcnt(0) lgkmcnt(0)" ::: "memory");
	v_ashrrev_i32_e32 v113, 31, v112
	v_ashrrev_i32_e32 v119, 31, v118
	v_ashrrev_i32_e32 v117, 31, v116
	v_ashrrev_i32_e32 v123, 31, v122
	v_ashrrev_i32_e32 v121, 31, v120
	v_ashrrev_i32_e32 v127, 31, v126
	v_ashrrev_i32_e32 v125, 31, v124
	v_ashrrev_i32_e32 v131, 31, v130
	v_ashrrev_i32_e32 v129, 31, v128
	v_ashrrev_i32_e32 v135, 31, v134
	v_ashrrev_i32_e32 v133, 31, v132
	v_ashrrev_i32_e32 v139, 31, v138
	v_ashrrev_i32_e32 v137, 31, v136
	v_ashrrev_i32_e32 v143, 31, v142
	v_ashrrev_i32_e32 v141, 31, v140
	v_lshlrev_b64 v[114:115], 13, v[114:115]
	v_lshlrev_b64 v[112:113], 13, v[112:113]
	v_lshlrev_b64 v[116:117], 13, v[116:117]
	v_lshlrev_b64 v[118:119], 13, v[118:119]
	v_lshlrev_b64 v[120:121], 13, v[120:121]
	v_lshlrev_b64 v[122:123], 13, v[122:123]
	v_lshlrev_b64 v[124:125], 13, v[124:125]
	v_lshlrev_b64 v[126:127], 13, v[126:127]
	v_lshlrev_b64 v[128:129], 13, v[128:129]
	v_lshlrev_b64 v[130:131], 13, v[130:131]
	v_lshlrev_b64 v[132:133], 13, v[132:133]
	v_lshlrev_b64 v[134:135], 13, v[134:135]
	v_lshlrev_b64 v[136:137], 13, v[136:137]
	v_lshlrev_b64 v[138:139], 13, v[138:139]
	v_lshlrev_b64 v[140:141], 13, v[140:141]
	v_lshlrev_b64 v[142:143], 13, v[142:143]
	v_lshl_add_u64 v[114:115], v[28:29], 0, v[114:115]
	v_lshl_add_u64 v[112:113], v[28:29], 0, v[112:113]
	v_lshl_add_u64 v[118:119], v[28:29], 0, v[118:119]
	v_lshl_add_u64 v[116:117], v[28:29], 0, v[116:117]
	v_lshl_add_u64 v[122:123], v[28:29], 0, v[122:123]
	v_lshl_add_u64 v[120:121], v[28:29], 0, v[120:121]
	v_lshl_add_u64 v[126:127], v[28:29], 0, v[126:127]
	v_lshl_add_u64 v[124:125], v[28:29], 0, v[124:125]
	v_lshl_add_u64 v[130:131], v[28:29], 0, v[130:131]
	v_lshl_add_u64 v[128:129], v[28:29], 0, v[128:129]
	v_lshl_add_u64 v[134:135], v[28:29], 0, v[134:135]
	v_lshl_add_u64 v[132:133], v[28:29], 0, v[132:133]
	v_lshl_add_u64 v[138:139], v[28:29], 0, v[138:139]
	v_lshl_add_u64 v[136:137], v[28:29], 0, v[136:137]
	v_lshl_add_u64 v[142:143], v[28:29], 0, v[142:143]
	v_lshl_add_u64 v[140:141], v[28:29], 0, v[140:141]
	global_load_dword v144, v[114:115], off
	global_load_dword v145, v[112:113], off
	global_load_dword v146, v[118:119], off
	global_load_dword v147, v[116:117], off
	global_load_dword v148, v[122:123], off
	global_load_dword v149, v[120:121], off
	global_load_dword v150, v[126:127], off
	global_load_dword v151, v[124:125], off
	global_load_dword v152, v[130:131], off
	global_load_dword v153, v[128:129], off
	global_load_dword v154, v[134:135], off
	global_load_dword v155, v[132:133], off
	global_load_dword v156, v[138:139], off
	global_load_dword v157, v[136:137], off
	global_load_dword v158, v[142:143], off
	global_load_dword v159, v[140:141], off
	s_add_i32 s4, s4, 16
	s_add_i32 s3, s3, 16
	s_add_i32 s5, s5, -16
	v_add_u32_e32 v112, s17, v4
	v_add_u32_e32 v114, s19, v1
	v_add_u32_e32 v118, s19, v3
	v_add_u32_e32 v116, s17, v6
	v_add_u32_e32 v122, s19, v5
	v_add_u32_e32 v120, s17, v8
	v_add_u32_e32 v126, s19, v7
	v_add_u32_e32 v124, s17, v10
	v_add_u32_e32 v130, s19, v9
	v_add_u32_e32 v128, s17, v12
	v_add_u32_e32 v134, s19, v11
	v_add_u32_e32 v132, s17, v14
	v_add_u32_e32 v138, s19, v13
	v_add_u32_e32 v136, s17, v16
	v_add_u32_e32 v142, s19, v15
	v_add_u32_e32 v140, s17, v18
	s_cmp_eq_u32 s5, 0
	v_mad_u64_u32 v[112:113], s[20:21], v112, s57, v[22:23]
	v_mad_u64_u32 v[114:115], s[20:21], v114, s57, v[22:23]
	v_mad_u64_u32 v[116:117], s[20:21], v116, s57, v[22:23]
	v_mad_u64_u32 v[118:119], s[20:21], v118, s57, v[22:23]
	v_mad_u64_u32 v[120:121], s[20:21], v120, s57, v[22:23]
	v_mad_u64_u32 v[122:123], s[20:21], v122, s57, v[22:23]
	v_mad_u64_u32 v[124:125], s[20:21], v124, s57, v[22:23]
	v_mad_u64_u32 v[126:127], s[20:21], v126, s57, v[22:23]
	v_mad_u64_u32 v[128:129], s[20:21], v128, s57, v[22:23]
	v_mad_u64_u32 v[130:131], s[20:21], v130, s57, v[22:23]
	v_mad_u64_u32 v[132:133], s[20:21], v132, s57, v[22:23]
	v_mad_u64_u32 v[134:135], s[20:21], v134, s57, v[22:23]
	v_mad_u64_u32 v[136:137], s[20:21], v136, s57, v[22:23]
	v_mad_u64_u32 v[138:139], s[20:21], v138, s57, v[22:23]
	v_mad_u64_u32 v[140:141], s[20:21], v140, s57, v[22:23]
	v_mad_u64_u32 v[142:143], s[20:21], v142, s57, v[22:23]
	s_waitcnt vmcnt(16)
	ds_write_b32 v46, v78
	ds_write_b32 v48, v79
	ds_write_b32 v50, v80
	ds_write_b32 v52, v81
	ds_write_b32 v54, v82
	ds_write_b32 v56, v83
	ds_write_b32 v58, v84
	ds_write_b32 v60, v85
	ds_write_b32 v62, v86
	ds_write_b32 v64, v87
	ds_write_b32 v66, v88
	ds_write_b32 v68, v89
	ds_write_b32 v70, v90
	ds_write_b32 v72, v91
	ds_write_b32 v74, v92
	ds_write_b32 v76, v93
	s_waitcnt vmcnt(0)
	ds_write_b32 v112, v144
	ds_write_b32 v114, v145
	ds_write_b32 v116, v146
	ds_write_b32 v118, v147
	ds_write_b32 v120, v148
	ds_write_b32 v122, v149
	ds_write_b32 v124, v150
	ds_write_b32 v126, v151
	ds_write_b32 v128, v152
	ds_write_b32 v130, v153
	ds_write_b32 v132, v154
	ds_write_b32 v134, v155
	ds_write_b32 v136, v156
	ds_write_b32 v138, v157
	ds_write_b32 v140, v158
	ds_write_b32 v142, v159
	s_branch .LBB0_109

; #define LAS __attribute__((address_space(3)))
; __device__ __forceinline__ void tr_item(const float* W, int N, bf16* WT, int ldk, int k0, int scol0, int drow0, LAS float* scr, int lane) {
;     if (scol0 >= 0) {
; #pragma unroll 8
;         for (int i = 0; i < 32; ++i) { const int kk = 2 * i + (lane >> 5); scr[kk * 33 + (lane & 31)] = W[(size_t)(k0 + kk) * N + scol0 + (lane & 31)]; }
;     } else {
; #pragma unroll 8
;         for (int i = 0; i < 32; ++i) { const int kk = 2 * i + (lane >> 5); scr[kk * 33 + (lane & 31)] = 0.f; }
;     }
;     asm volatile("s_waitcnt vmcnt(0) lgkmcnt(0)" ::: "memory");
.LBB0_136:
	s_lshl_b32 s19, s4, 1
	s_lshl_b32 s22, s3, 1
	v_add_u32_e32 v46, s19, v30
	v_add_u32_e32 v48, s22, v17
	v_add_u32_e32 v52, s22, v19
	v_add_u32_e32 v50, s19, v32
	v_add_u32_e32 v56, s22, v21
	v_add_u32_e32 v54, s19, v34
	v_add_u32_e32 v60, s22, v23
	v_add_u32_e32 v58, s19, v36
	v_add_u32_e32 v64, s22, v31
	v_add_u32_e32 v62, s19, v38
	v_add_u32_e32 v68, s22, v33
	v_add_u32_e32 v66, s19, v40
	v_add_u32_e32 v72, s22, v35
	v_add_u32_e32 v70, s19, v42
	v_add_u32_e32 v76, s22, v37
	v_add_u32_e32 v74, s19, v44
	v_mad_i64_i32 v[46:47], s[20:21], v46, s41, v[28:29]
	v_mad_i64_i32 v[48:49], s[20:21], v48, s41, v[28:29]
	v_mad_i64_i32 v[50:51], s[20:21], v50, s41, v[28:29]
	v_mad_i64_i32 v[52:53], s[20:21], v52, s41, v[28:29]
	v_mad_i64_i32 v[54:55], s[20:21], v54, s41, v[28:29]
	v_mad_i64_i32 v[56:57], s[20:21], v56, s41, v[28:29]
	v_mad_i64_i32 v[58:59], s[20:21], v58, s41, v[28:29]
	v_mad_i64_i32 v[60:61], s[20:21], v60, s41, v[28:29]
	v_mad_i64_i32 v[62:63], s[20:21], v62, s41, v[28:29]
	v_mad_i64_i32 v[64:65], s[20:21], v64, s41, v[28:29]
	v_mad_i64_i32 v[66:67], s[20:21], v66, s41, v[28:29]
	v_mad_i64_i32 v[68:69], s[20:21], v68, s41, v[28:29]
	v_mad_i64_i32 v[70:71], s[20:21], v70, s41, v[28:29]
	v_mad_i64_i32 v[72:73], s[20:21], v72, s41, v[28:29]
	v_mad_i64_i32 v[74:75], s[20:21], v74, s41, v[28:29]
	v_mad_i64_i32 v[76:77], s[20:21], v76, s41, v[28:29]
	global_load_dword v78, v[46:47], off
	global_load_dword v79, v[48:49], off
	global_load_dword v80, v[50:51], off
	global_load_dword v81, v[52:53], off
	global_load_dword v82, v[54:55], off
	global_load_dword v83, v[56:57], off
	global_load_dword v84, v[58:59], off
	global_load_dword v85, v[60:61], off
	global_load_dword v86, v[62:63], off
	global_load_dword v87, v[64:65], off
	global_load_dword v88, v[66:67], off
	global_load_dword v89, v[68:69], off
	global_load_dword v90, v[70:71], off
	global_load_dword v91, v[72:73], off
	global_load_dword v92, v[74:75], off
	global_load_dword v93, v[76:77], off
	s_add_i32 s4, s4, 16
	s_add_i32 s3, s3, 16
	s_add_i32 s5, s5, -16
	v_add_u32_e32 v46, s19, v4
	v_add_u32_e32 v48, s22, v1
	v_add_u32_e32 v52, s22, v3
	v_add_u32_e32 v50, s19, v6
	v_add_u32_e32 v56, s22, v5
	v_add_u32_e32 v54, s19, v8
	v_add_u32_e32 v60, s22, v7
	v_add_u32_e32 v58, s19, v10
	v_add_u32_e32 v64, s22, v9
	v_add_u32_e32 v62, s19, v12
	v_add_u32_e32 v68, s22, v11
	v_add_u32_e32 v66, s19, v14
	v_add_u32_e32 v72, s22, v13
	v_add_u32_e32 v70, s19, v16
	v_add_u32_e32 v76, s22, v15
	v_add_u32_e32 v74, s19, v18
	s_cmp_eq_u32 s5, 0
	v_mad_u64_u32 v[46:47], s[20:21], v46, s57, v[22:23]
	v_mad_u64_u32 v[48:49], s[20:21], v48, s57, v[22:23]
	v_mad_u64_u32 v[50:51], s[20:21], v50, s57, v[22:23]
	v_mad_u64_u32 v[52:53], s[20:21], v52, s57, v[22:23]
	v_mad_u64_u32 v[54:55], s[20:21], v54, s57, v[22:23]
	v_mad_u64_u32 v[56:57], s[20:21], v56, s57, v[22:23]
	v_mad_u64_u32 v[58:59], s[20:21], v58, s57, v[22:23]
	v_mad_u64_u32 v[60:61], s[20:21], v60, s57, v[22:23]
	v_mad_u64_u32 v[62:63], s[20:21], v62, s57, v[22:23]
	v_mad_u64_u32 v[64:65], s[20:21], v64, s57, v[22:23]
	v_mad_u64_u32 v[66:67], s[20:21], v66, s57, v[22:23]
	v_mad_u64_u32 v[68:69], s[20:21], v68, s57, v[22:23]
	v_mad_u64_u32 v[70:71], s[20:21], v70, s57, v[22:23]
	v_mad_u64_u32 v[72:73], s[20:21], v72, s57, v[22:23]
	v_mad_u64_u32 v[74:75], s[20:21], v74, s57, v[22:23]
	v_mad_u64_u32 v[76:77], s[20:21], v76, s57, v[22:23]
	s_lshl_b32 s19, s4, 1
	s_lshl_b32 s22, s3, 1
	v_add_u32_e32 v112, s19, v30
	v_add_u32_e32 v114, s22, v17
	v_add_u32_e32 v118, s22, v19
	v_add_u32_e32 v116, s19, v32
	v_add_u32_e32 v122, s22, v21
	v_add_u32_e32 v120, s19, v34
	v_add_u32_e32 v126, s22, v23
	v_add_u32_e32 v124, s19, v36
	v_add_u32_e32 v130, s22, v31
	v_add_u32_e32 v128, s19, v38
	v_add_u32_e32 v134, s22, v33
	v_add_u32_e32 v132, s19, v40
	v_add_u32_e32 v138, s22, v35
	v_add_u32_e32 v136, s19, v42
	v_add_u32_e32 v142, s22, v37
	v_add_u32_e32 v140, s19, v44
	v_mad_i64_i32 v[112:113], s[20:21], v112, s41, v[28:29]
	v_mad_i64_i32 v[114:115], s[20:21], v114, s41, v[28:29]
	v_mad_i64_i32 v[116:117], s[20:21], v116, s41, v[28:29]
	v_mad_i64_i32 v[118:119], s[20:21], v118, s41, v[28:29]
	v_mad_i64_i32 v[120:121], s[20:21], v120, s41, v[28:29]
	v_mad_i64_i32 v[122:123], s[20:21], v122, s41, v[28:29]
	v_mad_i64_i32 v[124:125], s[20:21], v124, s41, v[28:29]
	v_mad_i64_i32 v[126:127], s[20:21], v126, s41, v[28:29]
	v_mad_i64_i32 v[128:129], s[20:21], v128, s41, v[28:29]
	v_mad_i64_i32 v[130:131], s[20:21], v130, s41, v[28:29]
	v_mad_i64_i32 v[132:133], s[20:21], v132, s41, v[28:29]
	v_mad_i64_i32 v[134:135], s[20:21], v134, s41, v[28:29]
	v_mad_i64_i32 v[136:137], s[20:21], v136, s41, v[28:29]
	v_mad_i64_i32 v[138:139], s[20:21], v138, s41, v[28:29]
	v_mad_i64_i32 v[140:141], s[20:21], v140, s41, v[28:29]
	v_mad_i64_i32 v[142:143], s[20:21], v142, s41, v[28:29]
	global_load_dword v144, v[112:113], off
	global_load_dword v145, v[114:115], off
	global_load_dword v146, v[116:117], off
	global_load_dword v147, v[118:119], off
	global_load_dword v148, v[120:121], off
	global_load_dword v149, v[122:123], off
	global_load_dword v150, v[124:125], off
	global_load_dword v151, v[126:127], off
	global_load_dword v152, v[128:129], off
	global_load_dword v153, v[130:131], off
	global_load_dword v154, v[132:133], off
	global_load_dword v155, v[134:135], off
	global_load_dword v156, v[136:137], off
	global_load_dword v157, v[138:139], off
	global_load_dword v158, v[140:141], off
	global_load_dword v159, v[142:143], off
	s_add_i32 s4, s4, 16
	s_add_i32 s3, s3, 16
	s_add_i32 s5, s5, -16
	v_add_u32_e32 v112, s19, v4
	v_add_u32_e32 v114, s22, v1
	v_add_u32_e32 v118, s22, v3
	v_add_u32_e32 v116, s19, v6
	v_add_u32_e32 v122, s22, v5
	v_add_u32_e32 v120, s19, v8
	v_add_u32_e32 v126, s22, v7
	v_add_u32_e32 v124, s19, v10
	v_add_u32_e32 v130, s22, v9
	v_add_u32_e32 v128, s19, v12
	v_add_u32_e32 v134, s22, v11
	v_add_u32_e32 v132, s19, v14
	v_add_u32_e32 v138, s22, v13
	v_add_u32_e32 v136, s19, v16
	v_add_u32_e32 v142, s22, v15
	v_add_u32_e32 v140, s19, v18
	s_cmp_eq_u32 s5, 0
	v_mad_u64_u32 v[112:113], s[20:21], v112, s57, v[22:23]
	v_mad_u64_u32 v[114:115], s[20:21], v114, s57, v[22:23]
	v_mad_u64_u32 v[116:117], s[20:21], v116, s57, v[22:23]
	v_mad_u64_u32 v[118:119], s[20:21], v118, s57, v[22:23]
	v_mad_u64_u32 v[120:121], s[20:21], v120, s57, v[22:23]
	v_mad_u64_u32 v[122:123], s[20:21], v122, s57, v[22:23]
	v_mad_u64_u32 v[124:125], s[20:21], v124, s57, v[22:23]
	v_mad_u64_u32 v[126:127], s[20:21], v126, s57, v[22:23]
	v_mad_u64_u32 v[128:129], s[20:21], v128, s57, v[22:23]
	v_mad_u64_u32 v[130:131], s[20:21], v130, s57, v[22:23]
	v_mad_u64_u32 v[132:133], s[20:21], v132, s57, v[22:23]
	v_mad_u64_u32 v[134:135], s[20:21], v134, s57, v[22:23]
	v_mad_u64_u32 v[136:137], s[20:21], v136, s57, v[22:23]
	v_mad_u64_u32 v[138:139], s[20:21], v138, s57, v[22:23]
	v_mad_u64_u32 v[140:141], s[20:21], v140, s57, v[22:23]
	v_mad_u64_u32 v[142:143], s[20:21], v142, s57, v[22:23]
	s_waitcnt vmcnt(16)
; __device__ __forceinline__ void tr_item(const float* W, int N, bf16* WT, int ldk, int k0, int scol0, int drow0, LAS float* scr, int lane) {
;     ...
;         for (int i = 0; i < 32; ++i) { const int kk = 2 * i + (lane >> 5); scr[kk * 33 + (lane & 31)] = W[(size_t)(k0 + kk) * N + scol0 + (lane & 31)]; }
;     } else {
; #pragma unroll 8
;         for (int i = 0; i < 32; ++i) { const int kk = 2 * i + (lane >> 5); scr[kk * 33 + (lane & 31)] = 0.f; }
;     }
;     asm volatile("s_waitcnt vmcnt(0) lgkmcnt(0)" ::: "memory");
	ds_write_b32 v46, v78
	ds_write_b32 v48, v79
	ds_write_b32 v50, v80
	ds_write_b32 v52, v81
	ds_write_b32 v54, v82
	ds_write_b32 v56, v83
	ds_write_b32 v58, v84
	ds_write_b32 v60, v85
	ds_write_b32 v62, v86
	ds_write_b32 v64, v87
	ds_write_b32 v66, v88
	ds_write_b32 v68, v89
	ds_write_b32 v70, v90
	ds_write_b32 v72, v91
	ds_write_b32 v74, v92
	ds_write_b32 v76, v93
	s_waitcnt vmcnt(0)
	ds_write_b32 v112, v144
	ds_write_b32 v114, v145
	ds_write_b32 v116, v146
	ds_write_b32 v118, v147
	ds_write_b32 v120, v148
	ds_write_b32 v122, v149
	ds_write_b32 v124, v150
	ds_write_b32 v126, v151
	ds_write_b32 v128, v152
	ds_write_b32 v130, v153
	ds_write_b32 v132, v154
	ds_write_b32 v134, v155
	ds_write_b32 v136, v156
	ds_write_b32 v138, v157
	ds_write_b32 v140, v158
	ds_write_b32 v142, v159
	s_branch .LBB0_119

; #define LAS __attribute__((address_space(3)))
; __device__ __forceinline__ void tr_item(const float* W, int N, bf16* WT, int ldk, int k0, int scol0, int drow0, LAS float* scr, int lane) {
;     if (scol0 >= 0) {
; #pragma unroll 8
;         for (int i = 0; i < 32; ++i) { const int kk = 2 * i + (lane >> 5); scr[kk * 33 + (lane & 31)] = W[(size_t)(k0 + kk) * N + scol0 + (lane & 31)]; }
;     } else {
; #pragma unroll 8
;         for (int i = 0; i < 32; ++i) { const int kk = 2 * i + (lane >> 5); scr[kk * 33 + (lane & 31)] = 0.f; }
;     }
;     asm volatile("s_waitcnt vmcnt(0) lgkmcnt(0)" ::: "memory");
.LBB0_146:
	s_lshl_b32 s20, s16, 1
	s_lshl_b32 s21, s5, 1
	v_add_u32_e32 v48, s20, v30
	v_add_u32_e32 v46, s21, v17
	v_add_u32_e32 v50, s21, v19
	v_add_u32_e32 v52, s20, v32
	v_add_u32_e32 v54, s21, v21
	v_add_u32_e32 v56, s20, v34
	v_add_u32_e32 v58, s21, v23
	v_add_u32_e32 v60, s20, v36
	v_add_u32_e32 v62, s21, v31
	v_add_u32_e32 v64, s20, v38
	v_add_u32_e32 v66, s21, v33
	v_add_u32_e32 v68, s20, v40
	v_add_u32_e32 v70, s21, v35
	v_add_u32_e32 v72, s20, v42
	v_add_u32_e32 v74, s21, v37
	v_add_u32_e32 v76, s20, v44
	v_ashrrev_i32_e32 v49, 31, v48
	v_ashrrev_i32_e32 v47, 31, v46
	v_ashrrev_i32_e32 v53, 31, v52
	v_ashrrev_i32_e32 v51, 31, v50
	v_ashrrev_i32_e32 v57, 31, v56
	v_ashrrev_i32_e32 v55, 31, v54
	v_ashrrev_i32_e32 v61, 31, v60
	v_ashrrev_i32_e32 v59, 31, v58
	v_ashrrev_i32_e32 v65, 31, v64
	v_ashrrev_i32_e32 v63, 31, v62
	v_ashrrev_i32_e32 v69, 31, v68
	v_ashrrev_i32_e32 v67, 31, v66
	v_ashrrev_i32_e32 v73, 31, v72
	v_ashrrev_i32_e32 v71, 31, v70
	v_ashrrev_i32_e32 v77, 31, v76
	v_ashrrev_i32_e32 v75, 31, v74
	v_lshlrev_b64 v[48:49], 13, v[48:49]
	v_lshlrev_b64 v[46:47], 13, v[46:47]
	v_lshlrev_b64 v[50:51], 13, v[50:51]
	v_lshlrev_b64 v[52:53], 13, v[52:53]
	v_lshlrev_b64 v[54:55], 13, v[54:55]
	v_lshlrev_b64 v[56:57], 13, v[56:57]
	v_lshlrev_b64 v[58:59], 13, v[58:59]
	v_lshlrev_b64 v[60:61], 13, v[60:61]
	v_lshlrev_b64 v[62:63], 13, v[62:63]
	v_lshlrev_b64 v[64:65], 13, v[64:65]
	v_lshlrev_b64 v[66:67], 13, v[66:67]
	v_lshlrev_b64 v[68:69], 13, v[68:69]
	v_lshlrev_b64 v[70:71], 13, v[70:71]
	v_lshlrev_b64 v[72:73], 13, v[72:73]
	v_lshlrev_b64 v[74:75], 13, v[74:75]
	v_lshlrev_b64 v[76:77], 13, v[76:77]
	v_lshl_add_u64 v[48:49], v[28:29], 0, v[48:49]
	v_lshl_add_u64 v[46:47], v[28:29], 0, v[46:47]
	v_lshl_add_u64 v[52:53], v[28:29], 0, v[52:53]
	v_lshl_add_u64 v[50:51], v[28:29], 0, v[50:51]
	v_lshl_add_u64 v[56:57], v[28:29], 0, v[56:57]
	v_lshl_add_u64 v[54:55], v[28:29], 0, v[54:55]
	v_lshl_add_u64 v[60:61], v[28:29], 0, v[60:61]
	v_lshl_add_u64 v[58:59], v[28:29], 0, v[58:59]
	v_lshl_add_u64 v[64:65], v[28:29], 0, v[64:65]
	v_lshl_add_u64 v[62:63], v[28:29], 0, v[62:63]
	v_lshl_add_u64 v[68:69], v[28:29], 0, v[68:69]
	v_lshl_add_u64 v[66:67], v[28:29], 0, v[66:67]
	v_lshl_add_u64 v[72:73], v[28:29], 0, v[72:73]
	v_lshl_add_u64 v[70:71], v[28:29], 0, v[70:71]
	v_lshl_add_u64 v[76:77], v[28:29], 0, v[76:77]
	v_lshl_add_u64 v[74:75], v[28:29], 0, v[74:75]
	global_load_dword v78, v[48:49], off
	global_load_dword v79, v[46:47], off
	global_load_dword v80, v[52:53], off
	global_load_dword v81, v[50:51], off
	global_load_dword v82, v[56:57], off
	global_load_dword v83, v[54:55], off
	global_load_dword v84, v[60:61], off
	global_load_dword v85, v[58:59], off
	global_load_dword v86, v[64:65], off
	global_load_dword v87, v[62:63], off
	global_load_dword v88, v[68:69], off
	global_load_dword v89, v[66:67], off
	global_load_dword v90, v[72:73], off
	global_load_dword v91, v[70:71], off
	global_load_dword v92, v[76:77], off
	global_load_dword v93, v[74:75], off
	s_add_i32 s16, s16, 16
	s_add_i32 s5, s5, 16
	s_add_i32 s17, s17, -16
	v_add_u32_e32 v46, s20, v4
	v_add_u32_e32 v48, s21, v1
	v_add_u32_e32 v52, s21, v3
	v_add_u32_e32 v50, s20, v6
	v_add_u32_e32 v56, s21, v5
	v_add_u32_e32 v54, s20, v8
	v_add_u32_e32 v60, s21, v7
	v_add_u32_e32 v58, s20, v10
	v_add_u32_e32 v64, s21, v9
	v_add_u32_e32 v62, s20, v12
	v_add_u32_e32 v68, s21, v11
	v_add_u32_e32 v66, s20, v14
	v_add_u32_e32 v72, s21, v13
	v_add_u32_e32 v70, s20, v16
	v_add_u32_e32 v76, s21, v15
	v_add_u32_e32 v74, s20, v18
	s_cmp_eq_u32 s17, 0
	v_mad_u64_u32 v[46:47], s[20:21], v46, s57, v[22:23]
	v_mad_u64_u32 v[48:49], s[20:21], v48, s57, v[22:23]
	v_mad_u64_u32 v[50:51], s[20:21], v50, s57, v[22:23]
	v_mad_u64_u32 v[52:53], s[20:21], v52, s57, v[22:23]
	v_mad_u64_u32 v[54:55], s[20:21], v54, s57, v[22:23]
	v_mad_u64_u32 v[56:57], s[20:21], v56, s57, v[22:23]
	v_mad_u64_u32 v[58:59], s[20:21], v58, s57, v[22:23]
	v_mad_u64_u32 v[60:61], s[20:21], v60, s57, v[22:23]
	v_mad_u64_u32 v[62:63], s[20:21], v62, s57, v[22:23]
	v_mad_u64_u32 v[64:65], s[20:21], v64, s57, v[22:23]
	v_mad_u64_u32 v[66:67], s[20:21], v66, s57, v[22:23]
	v_mad_u64_u32 v[68:69], s[20:21], v68, s57, v[22:23]
	v_mad_u64_u32 v[70:71], s[20:21], v70, s57, v[22:23]
	v_mad_u64_u32 v[72:73], s[20:21], v72, s57, v[22:23]
	v_mad_u64_u32 v[74:75], s[20:21], v74, s57, v[22:23]
	v_mad_u64_u32 v[76:77], s[20:21], v76, s57, v[22:23]
	s_lshl_b32 s20, s16, 1
	s_lshl_b32 s21, s5, 1
	v_add_u32_e32 v114, s20, v30
	v_add_u32_e32 v112, s21, v17
	v_add_u32_e32 v116, s21, v19
	v_add_u32_e32 v118, s20, v32
	v_add_u32_e32 v120, s21, v21
	v_add_u32_e32 v122, s20, v34
	v_add_u32_e32 v124, s21, v23
	v_add_u32_e32 v126, s20, v36
	v_add_u32_e32 v128, s21, v31
	v_add_u32_e32 v130, s20, v38
	v_add_u32_e32 v132, s21, v33
	v_add_u32_e32 v134, s20, v40
	v_add_u32_e32 v136, s21, v35
	v_add_u32_e32 v138, s20, v42
	v_add_u32_e32 v140, s21, v37
	v_add_u32_e32 v142, s20, v44
	v_ashrrev_i32_e32 v115, 31, v114
; #define LAS __attribute__((address_space(3)))
; __device__ __forceinline__ void tr_item(const float* W, int N, bf16* WT, int ldk, int k0, int scol0, int drow0, LAS float* scr, int lane) {
;     if (scol0 >= 0) {
; #pragma unroll 8
;         for (int i = 0; i < 32; ++i) { const int kk = 2 * i + (lane >> 5); scr[kk * 33 + (lane & 31)] = W[(size_t)(k0 + kk) * N + scol0 + (lane & 31)]; }
;     } else {
; #pragma unroll 8
;         for (int i = 0; i < 32; ++i) { const int kk = 2 * i + (lane >> 5); scr[kk * 33 + (lane & 31)] = 0.f; }
;     }
;     asm volatile("s_waitcnt vmcnt(0) lgkmcnt(0)" ::: "memory");
	v_ashrrev_i32_e32 v113, 31, v112
	v_ashrrev_i32_e32 v119, 31, v118
	v_ashrrev_i32_e32 v117, 31, v116
	v_ashrrev_i32_e32 v123, 31, v122
	v_ashrrev_i32_e32 v121, 31, v120
	v_ashrrev_i32_e32 v127, 31, v126
	v_ashrrev_i32_e32 v125, 31, v124
	v_ashrrev_i32_e32 v131, 31, v130
	v_ashrrev_i32_e32 v129, 31, v128
	v_ashrrev_i32_e32 v135, 31, v134
	v_ashrrev_i32_e32 v133, 31, v132
	v_ashrrev_i32_e32 v139, 31, v138
	v_ashrrev_i32_e32 v137, 31, v136
	v_ashrrev_i32_e32 v143, 31, v142
	v_ashrrev_i32_e32 v141, 31, v140
	v_lshlrev_b64 v[114:115], 13, v[114:115]
	v_lshlrev_b64 v[112:113], 13, v[112:113]
	v_lshlrev_b64 v[116:117], 13, v[116:117]
	v_lshlrev_b64 v[118:119], 13, v[118:119]
	v_lshlrev_b64 v[120:121], 13, v[120:121]
	v_lshlrev_b64 v[122:123], 13, v[122:123]
	v_lshlrev_b64 v[124:125], 13, v[124:125]
	v_lshlrev_b64 v[126:127], 13, v[126:127]
	v_lshlrev_b64 v[128:129], 13, v[128:129]
	v_lshlrev_b64 v[130:131], 13, v[130:131]
	v_lshlrev_b64 v[132:133], 13, v[132:133]
	v_lshlrev_b64 v[134:135], 13, v[134:135]
	v_lshlrev_b64 v[136:137], 13, v[136:137]
	v_lshlrev_b64 v[138:139], 13, v[138:139]
	v_lshlrev_b64 v[140:141], 13, v[140:141]
	v_lshlrev_b64 v[142:143], 13, v[142:143]
	v_lshl_add_u64 v[114:115], v[28:29], 0, v[114:115]
	v_lshl_add_u64 v[112:113], v[28:29], 0, v[112:113]
	v_lshl_add_u64 v[118:119], v[28:29], 0, v[118:119]
	v_lshl_add_u64 v[116:117], v[28:29], 0, v[116:117]
	v_lshl_add_u64 v[122:123], v[28:29], 0, v[122:123]
	v_lshl_add_u64 v[120:121], v[28:29], 0, v[120:121]
	v_lshl_add_u64 v[126:127], v[28:29], 0, v[126:127]
	v_lshl_add_u64 v[124:125], v[28:29], 0, v[124:125]
	v_lshl_add_u64 v[130:131], v[28:29], 0, v[130:131]
	v_lshl_add_u64 v[128:129], v[28:29], 0, v[128:129]
	v_lshl_add_u64 v[134:135], v[28:29], 0, v[134:135]
	v_lshl_add_u64 v[132:133], v[28:29], 0, v[132:133]
	v_lshl_add_u64 v[138:139], v[28:29], 0, v[138:139]
	v_lshl_add_u64 v[136:137], v[28:29], 0, v[136:137]
	v_lshl_add_u64 v[142:143], v[28:29], 0, v[142:143]
	v_lshl_add_u64 v[140:141], v[28:29], 0, v[140:141]
	global_load_dword v144, v[114:115], off
	global_load_dword v145, v[112:113], off
	global_load_dword v146, v[118:119], off
	global_load_dword v147, v[116:117], off
	global_load_dword v148, v[122:123], off
	global_load_dword v149, v[120:121], off
	global_load_dword v150, v[126:127], off
	global_load_dword v151, v[124:125], off
	global_load_dword v152, v[130:131], off
	global_load_dword v153, v[128:129], off
	global_load_dword v154, v[134:135], off
	global_load_dword v155, v[132:133], off
	global_load_dword v156, v[138:139], off
	global_load_dword v157, v[136:137], off
	global_load_dword v158, v[142:143], off
	global_load_dword v159, v[140:141], off
	s_add_i32 s16, s16, 16
	s_add_i32 s5, s5, 16
	s_add_i32 s17, s17, -16
	v_add_u32_e32 v112, s20, v4
	v_add_u32_e32 v114, s21, v1
	v_add_u32_e32 v118, s21, v3
	v_add_u32_e32 v116, s20, v6
	v_add_u32_e32 v122, s21, v5
	v_add_u32_e32 v120, s20, v8
	v_add_u32_e32 v126, s21, v7
	v_add_u32_e32 v124, s20, v10
	v_add_u32_e32 v130, s21, v9
	v_add_u32_e32 v128, s20, v12
	v_add_u32_e32 v134, s21, v11
	v_add_u32_e32 v132, s20, v14
	v_add_u32_e32 v138, s21, v13
	v_add_u32_e32 v136, s20, v16
	v_add_u32_e32 v142, s21, v15
	v_add_u32_e32 v140, s20, v18
	s_cmp_eq_u32 s17, 0
	v_mad_u64_u32 v[112:113], s[20:21], v112, s57, v[22:23]
	v_mad_u64_u32 v[114:115], s[20:21], v114, s57, v[22:23]
	v_mad_u64_u32 v[116:117], s[20:21], v116, s57, v[22:23]
	v_mad_u64_u32 v[118:119], s[20:21], v118, s57, v[22:23]
	v_mad_u64_u32 v[120:121], s[20:21], v120, s57, v[22:23]
	v_mad_u64_u32 v[122:123], s[20:21], v122, s57, v[22:23]
	v_mad_u64_u32 v[124:125], s[20:21], v124, s57, v[22:23]
	v_mad_u64_u32 v[126:127], s[20:21], v126, s57, v[22:23]
	v_mad_u64_u32 v[128:129], s[20:21], v128, s57, v[22:23]
	v_mad_u64_u32 v[130:131], s[20:21], v130, s57, v[22:23]
	v_mad_u64_u32 v[132:133], s[20:21], v132, s57, v[22:23]
	v_mad_u64_u32 v[134:135], s[20:21], v134, s57, v[22:23]
	v_mad_u64_u32 v[136:137], s[20:21], v136, s57, v[22:23]
	v_mad_u64_u32 v[138:139], s[20:21], v138, s57, v[22:23]
	v_mad_u64_u32 v[140:141], s[20:21], v140, s57, v[22:23]
	v_mad_u64_u32 v[142:143], s[20:21], v142, s57, v[22:23]
	s_waitcnt vmcnt(16)
	ds_write_b32 v46, v78
	ds_write_b32 v48, v79
	ds_write_b32 v50, v80
	ds_write_b32 v52, v81
	ds_write_b32 v54, v82
	ds_write_b32 v56, v83
	ds_write_b32 v58, v84
	ds_write_b32 v60, v85
	ds_write_b32 v62, v86
	ds_write_b32 v64, v87
	ds_write_b32 v66, v88
	ds_write_b32 v68, v89
	ds_write_b32 v70, v90
	ds_write_b32 v72, v91
	ds_write_b32 v74, v92
	ds_write_b32 v76, v93
	s_waitcnt vmcnt(0)
	ds_write_b32 v112, v144
	ds_write_b32 v114, v145
	ds_write_b32 v116, v146
	ds_write_b32 v118, v147
	ds_write_b32 v120, v148
	ds_write_b32 v122, v149
	ds_write_b32 v124, v150
	ds_write_b32 v126, v151
	ds_write_b32 v128, v152
	ds_write_b32 v130, v153
	ds_write_b32 v132, v154
	ds_write_b32 v134, v155
	ds_write_b32 v136, v156
	ds_write_b32 v138, v157
	ds_write_b32 v140, v158
	ds_write_b32 v142, v159
	s_branch .LBB0_139

; #define LAS __attribute__((address_space(3)))
; __device__ __forceinline__ void tr_item(const float* W, int N, bf16* WT, int ldk, int k0, int scol0, int drow0, LAS float* scr, int lane) {
;     if (scol0 >= 0) {
; #pragma unroll 8
;         for (int i = 0; i < 32; ++i) { const int kk = 2 * i + (lane >> 5); scr[kk * 33 + (lane & 31)] = W[(size_t)(k0 + kk) * N + scol0 + (lane & 31)]; }
;     } else {
; #pragma unroll 8
;         for (int i = 0; i < 32; ++i) { const int kk = 2 * i + (lane >> 5); scr[kk * 33 + (lane & 31)] = 0.f; }
;     }
;     asm volatile("s_waitcnt vmcnt(0) lgkmcnt(0)" ::: "memory");
.LBB0_176:
	s_lshl_b32 s14, s4, 1
	s_lshl_b32 s15, s3, 1
	v_add_u32_e32 v46, s14, v28
	v_add_u32_e32 v44, s15, v17
	v_add_u32_e32 v48, s15, v19
	v_add_u32_e32 v50, s14, v30
	v_add_u32_e32 v52, s15, v23
	v_add_u32_e32 v54, s14, v32
	v_add_u32_e32 v56, s15, v29
	v_add_u32_e32 v58, s14, v34
	v_add_u32_e32 v60, s15, v31
	v_add_u32_e32 v62, s14, v36
	v_add_u32_e32 v64, s15, v33
	v_add_u32_e32 v66, s14, v38
	v_add_u32_e32 v68, s15, v35
	v_add_u32_e32 v70, s14, v40
	v_add_u32_e32 v72, s15, v37
	v_add_u32_e32 v74, s14, v42
	v_ashrrev_i32_e32 v47, 31, v46
	v_ashrrev_i32_e32 v45, 31, v44
	v_ashrrev_i32_e32 v51, 31, v50
	v_ashrrev_i32_e32 v49, 31, v48
	v_ashrrev_i32_e32 v55, 31, v54
	v_ashrrev_i32_e32 v53, 31, v52
	v_ashrrev_i32_e32 v59, 31, v58
	v_ashrrev_i32_e32 v57, 31, v56
	v_ashrrev_i32_e32 v63, 31, v62
	v_ashrrev_i32_e32 v61, 31, v60
	v_ashrrev_i32_e32 v67, 31, v66
	v_ashrrev_i32_e32 v65, 31, v64
	v_ashrrev_i32_e32 v71, 31, v70
	v_ashrrev_i32_e32 v69, 31, v68
	v_ashrrev_i32_e32 v75, 31, v74
	v_ashrrev_i32_e32 v73, 31, v72
	v_lshlrev_b64 v[46:47], 13, v[46:47]
	v_lshlrev_b64 v[44:45], 13, v[44:45]
	v_lshlrev_b64 v[48:49], 13, v[48:49]
	v_lshlrev_b64 v[50:51], 13, v[50:51]
	v_lshlrev_b64 v[52:53], 13, v[52:53]
	v_lshlrev_b64 v[54:55], 13, v[54:55]
	v_lshlrev_b64 v[56:57], 13, v[56:57]
	v_lshlrev_b64 v[58:59], 13, v[58:59]
	v_lshlrev_b64 v[60:61], 13, v[60:61]
	v_lshlrev_b64 v[62:63], 13, v[62:63]
	v_lshlrev_b64 v[64:65], 13, v[64:65]
	v_lshlrev_b64 v[66:67], 13, v[66:67]
	v_lshlrev_b64 v[68:69], 13, v[68:69]
	v_lshlrev_b64 v[70:71], 13, v[70:71]
	v_lshlrev_b64 v[72:73], 13, v[72:73]
	v_lshlrev_b64 v[74:75], 13, v[74:75]
	v_lshl_add_u64 v[46:47], v[26:27], 0, v[46:47]
	v_lshl_add_u64 v[44:45], v[26:27], 0, v[44:45]
	v_lshl_add_u64 v[50:51], v[26:27], 0, v[50:51]
	v_lshl_add_u64 v[48:49], v[26:27], 0, v[48:49]
	v_lshl_add_u64 v[54:55], v[26:27], 0, v[54:55]
	v_lshl_add_u64 v[52:53], v[26:27], 0, v[52:53]
	v_lshl_add_u64 v[58:59], v[26:27], 0, v[58:59]
	v_lshl_add_u64 v[56:57], v[26:27], 0, v[56:57]
	v_lshl_add_u64 v[62:63], v[26:27], 0, v[62:63]
	v_lshl_add_u64 v[60:61], v[26:27], 0, v[60:61]
	v_lshl_add_u64 v[66:67], v[26:27], 0, v[66:67]
	v_lshl_add_u64 v[64:65], v[26:27], 0, v[64:65]
	v_lshl_add_u64 v[70:71], v[26:27], 0, v[70:71]
	v_lshl_add_u64 v[68:69], v[26:27], 0, v[68:69]
	v_lshl_add_u64 v[74:75], v[26:27], 0, v[74:75]
	v_lshl_add_u64 v[72:73], v[26:27], 0, v[72:73]
	global_load_dword v43, v[46:47], off
	global_load_dword v76, v[44:45], off
	global_load_dword v77, v[50:51], off
	global_load_dword v78, v[48:49], off
	global_load_dword v79, v[54:55], off
	global_load_dword v80, v[52:53], off
	global_load_dword v81, v[58:59], off
	global_load_dword v82, v[56:57], off
	global_load_dword v83, v[62:63], off
	global_load_dword v84, v[60:61], off
	global_load_dword v85, v[66:67], off
	global_load_dword v86, v[64:65], off
	global_load_dword v87, v[70:71], off
	global_load_dword v88, v[68:69], off
	global_load_dword v89, v[74:75], off
	global_load_dword v90, v[72:73], off
	s_add_i32 s4, s4, 16
	s_add_i32 s3, s3, 16
	s_add_i32 s5, s5, -16
	v_add_u32_e32 v44, s14, v4
	v_add_u32_e32 v46, s15, v1
	v_add_u32_e32 v50, s15, v3
	v_add_u32_e32 v48, s14, v6
	v_add_u32_e32 v54, s15, v5
	v_add_u32_e32 v52, s14, v8
	v_add_u32_e32 v58, s15, v7
	v_add_u32_e32 v56, s14, v10
	v_add_u32_e32 v62, s15, v9
	v_add_u32_e32 v60, s14, v12
	v_add_u32_e32 v66, s15, v11
	v_add_u32_e32 v64, s14, v14
	v_add_u32_e32 v70, s15, v13
	v_add_u32_e32 v68, s14, v16
	v_add_u32_e32 v74, s15, v15
	v_add_u32_e32 v72, s14, v18
	s_cmp_eq_u32 s5, 0
	v_mad_u64_u32 v[44:45], s[14:15], v44, s57, v[22:23]
	v_mad_u64_u32 v[46:47], s[14:15], v46, s57, v[22:23]
	v_mad_u64_u32 v[48:49], s[14:15], v48, s57, v[22:23]
	v_mad_u64_u32 v[50:51], s[14:15], v50, s57, v[22:23]
	v_mad_u64_u32 v[52:53], s[14:15], v52, s57, v[22:23]
	v_mad_u64_u32 v[54:55], s[14:15], v54, s57, v[22:23]
	v_mad_u64_u32 v[56:57], s[14:15], v56, s57, v[22:23]
	v_mad_u64_u32 v[58:59], s[14:15], v58, s57, v[22:23]
	v_mad_u64_u32 v[60:61], s[14:15], v60, s57, v[22:23]
	v_mad_u64_u32 v[62:63], s[14:15], v62, s57, v[22:23]
	v_mad_u64_u32 v[64:65], s[14:15], v64, s57, v[22:23]
	v_mad_u64_u32 v[66:67], s[14:15], v66, s57, v[22:23]
	v_mad_u64_u32 v[68:69], s[14:15], v68, s57, v[22:23]
	v_mad_u64_u32 v[70:71], s[14:15], v70, s57, v[22:23]
	v_mad_u64_u32 v[72:73], s[14:15], v72, s57, v[22:23]
	v_mad_u64_u32 v[74:75], s[14:15], v74, s57, v[22:23]
	s_lshl_b32 s14, s4, 1
	s_lshl_b32 s15, s3, 1
	v_add_u32_e32 v116, s14, v28
	v_add_u32_e32 v114, s15, v17
	v_add_u32_e32 v118, s15, v19
	v_add_u32_e32 v120, s14, v30
	v_add_u32_e32 v122, s15, v23
	v_add_u32_e32 v124, s14, v32
	v_add_u32_e32 v126, s15, v29
	v_add_u32_e32 v128, s14, v34
	v_add_u32_e32 v130, s15, v31
	v_add_u32_e32 v132, s14, v36
	v_add_u32_e32 v134, s15, v33
	v_add_u32_e32 v136, s14, v38
	v_add_u32_e32 v138, s15, v35
	v_add_u32_e32 v140, s14, v40
	v_add_u32_e32 v142, s15, v37
	v_add_u32_e32 v144, s14, v42
	v_ashrrev_i32_e32 v117, 31, v116
; #define LAS __attribute__((address_space(3)))
; __device__ __forceinline__ void tr_item(const float* W, int N, bf16* WT, int ldk, int k0, int scol0, int drow0, LAS float* scr, int lane) {
;     if (scol0 >= 0) {
; #pragma unroll 8
;         for (int i = 0; i < 32; ++i) { const int kk = 2 * i + (lane >> 5); scr[kk * 33 + (lane & 31)] = W[(size_t)(k0 + kk) * N + scol0 + (lane & 31)]; }
;     } else {
; #pragma unroll 8
;         for (int i = 0; i < 32; ++i) { const int kk = 2 * i + (lane >> 5); scr[kk * 33 + (lane & 31)] = 0.f; }
;     }
;     asm volatile("s_waitcnt vmcnt(0) lgkmcnt(0)" ::: "memory");
	v_ashrrev_i32_e32 v115, 31, v114
	v_ashrrev_i32_e32 v121, 31, v120
	v_ashrrev_i32_e32 v119, 31, v118
	v_ashrrev_i32_e32 v125, 31, v124
	v_ashrrev_i32_e32 v123, 31, v122
	v_ashrrev_i32_e32 v129, 31, v128
	v_ashrrev_i32_e32 v127, 31, v126
	v_ashrrev_i32_e32 v133, 31, v132
	v_ashrrev_i32_e32 v131, 31, v130
	v_ashrrev_i32_e32 v137, 31, v136
	v_ashrrev_i32_e32 v135, 31, v134
	v_ashrrev_i32_e32 v141, 31, v140
	v_ashrrev_i32_e32 v139, 31, v138
	v_ashrrev_i32_e32 v145, 31, v144
	v_ashrrev_i32_e32 v143, 31, v142
	v_lshlrev_b64 v[116:117], 13, v[116:117]
	v_lshlrev_b64 v[114:115], 13, v[114:115]
	v_lshlrev_b64 v[118:119], 13, v[118:119]
	v_lshlrev_b64 v[120:121], 13, v[120:121]
	v_lshlrev_b64 v[122:123], 13, v[122:123]
	v_lshlrev_b64 v[124:125], 13, v[124:125]
	v_lshlrev_b64 v[126:127], 13, v[126:127]
	v_lshlrev_b64 v[128:129], 13, v[128:129]
	v_lshlrev_b64 v[130:131], 13, v[130:131]
	v_lshlrev_b64 v[132:133], 13, v[132:133]
	v_lshlrev_b64 v[134:135], 13, v[134:135]
	v_lshlrev_b64 v[136:137], 13, v[136:137]
	v_lshlrev_b64 v[138:139], 13, v[138:139]
	v_lshlrev_b64 v[140:141], 13, v[140:141]
	v_lshlrev_b64 v[142:143], 13, v[142:143]
	v_lshlrev_b64 v[144:145], 13, v[144:145]
	v_lshl_add_u64 v[116:117], v[26:27], 0, v[116:117]
	v_lshl_add_u64 v[114:115], v[26:27], 0, v[114:115]
	v_lshl_add_u64 v[120:121], v[26:27], 0, v[120:121]
	v_lshl_add_u64 v[118:119], v[26:27], 0, v[118:119]
	v_lshl_add_u64 v[124:125], v[26:27], 0, v[124:125]
	v_lshl_add_u64 v[122:123], v[26:27], 0, v[122:123]
	v_lshl_add_u64 v[128:129], v[26:27], 0, v[128:129]
	v_lshl_add_u64 v[126:127], v[26:27], 0, v[126:127]
	v_lshl_add_u64 v[132:133], v[26:27], 0, v[132:133]
	v_lshl_add_u64 v[130:131], v[26:27], 0, v[130:131]
	v_lshl_add_u64 v[136:137], v[26:27], 0, v[136:137]
	v_lshl_add_u64 v[134:135], v[26:27], 0, v[134:135]
	v_lshl_add_u64 v[140:141], v[26:27], 0, v[140:141]
	v_lshl_add_u64 v[138:139], v[26:27], 0, v[138:139]
	v_lshl_add_u64 v[144:145], v[26:27], 0, v[144:145]
	v_lshl_add_u64 v[142:143], v[26:27], 0, v[142:143]
	global_load_dword v113, v[116:117], off
	global_load_dword v146, v[114:115], off
	global_load_dword v147, v[120:121], off
	global_load_dword v148, v[118:119], off
	global_load_dword v149, v[124:125], off
	global_load_dword v150, v[122:123], off
	global_load_dword v151, v[128:129], off
	global_load_dword v152, v[126:127], off
	global_load_dword v153, v[132:133], off
	global_load_dword v154, v[130:131], off
	global_load_dword v155, v[136:137], off
	global_load_dword v156, v[134:135], off
	global_load_dword v157, v[140:141], off
	global_load_dword v158, v[138:139], off
	global_load_dword v159, v[144:145], off
	global_load_dword v160, v[142:143], off
	s_add_i32 s4, s4, 16
	s_add_i32 s3, s3, 16
	s_add_i32 s5, s5, -16
	v_add_u32_e32 v114, s14, v4
	v_add_u32_e32 v116, s15, v1
	v_add_u32_e32 v120, s15, v3
	v_add_u32_e32 v118, s14, v6
	v_add_u32_e32 v124, s15, v5
	v_add_u32_e32 v122, s14, v8
	v_add_u32_e32 v128, s15, v7
	v_add_u32_e32 v126, s14, v10
	v_add_u32_e32 v132, s15, v9
	v_add_u32_e32 v130, s14, v12
	v_add_u32_e32 v136, s15, v11
	v_add_u32_e32 v134, s14, v14
	v_add_u32_e32 v140, s15, v13
	v_add_u32_e32 v138, s14, v16
	v_add_u32_e32 v144, s15, v15
	v_add_u32_e32 v142, s14, v18
	s_cmp_eq_u32 s5, 0
	v_mad_u64_u32 v[114:115], s[14:15], v114, s57, v[22:23]
	v_mad_u64_u32 v[116:117], s[14:15], v116, s57, v[22:23]
	v_mad_u64_u32 v[118:119], s[14:15], v118, s57, v[22:23]
	v_mad_u64_u32 v[120:121], s[14:15], v120, s57, v[22:23]
	v_mad_u64_u32 v[122:123], s[14:15], v122, s57, v[22:23]
	v_mad_u64_u32 v[124:125], s[14:15], v124, s57, v[22:23]
	v_mad_u64_u32 v[126:127], s[14:15], v126, s57, v[22:23]
	v_mad_u64_u32 v[128:129], s[14:15], v128, s57, v[22:23]
	v_mad_u64_u32 v[130:131], s[14:15], v130, s57, v[22:23]
	v_mad_u64_u32 v[132:133], s[14:15], v132, s57, v[22:23]
	v_mad_u64_u32 v[134:135], s[14:15], v134, s57, v[22:23]
	v_mad_u64_u32 v[136:137], s[14:15], v136, s57, v[22:23]
	v_mad_u64_u32 v[138:139], s[14:15], v138, s57, v[22:23]
	v_mad_u64_u32 v[140:141], s[14:15], v140, s57, v[22:23]
	v_mad_u64_u32 v[142:143], s[14:15], v142, s57, v[22:23]
	v_mad_u64_u32 v[144:145], s[14:15], v144, s57, v[22:23]
	s_waitcnt vmcnt(16)
	ds_write_b32 v44, v43
	ds_write_b32 v46, v76
	ds_write_b32 v48, v77
	ds_write_b32 v50, v78
	ds_write_b32 v52, v79
	ds_write_b32 v54, v80
	ds_write_b32 v56, v81
	ds_write_b32 v58, v82
	ds_write_b32 v60, v83
	ds_write_b32 v62, v84
	ds_write_b32 v64, v85
	ds_write_b32 v66, v86
	ds_write_b32 v68, v87
	ds_write_b32 v70, v88
	ds_write_b32 v72, v89
	ds_write_b32 v74, v90
	s_waitcnt vmcnt(0)
	ds_write_b32 v114, v113
	ds_write_b32 v116, v146
	ds_write_b32 v118, v147
	ds_write_b32 v120, v148
	ds_write_b32 v122, v149
	ds_write_b32 v124, v150
	ds_write_b32 v126, v151
	ds_write_b32 v128, v152
	ds_write_b32 v130, v153
	ds_write_b32 v132, v154
	ds_write_b32 v134, v155
	ds_write_b32 v136, v156
	ds_write_b32 v138, v157
	ds_write_b32 v140, v158
	ds_write_b32 v142, v159
	ds_write_b32 v144, v160
	s_branch .LBB0_169

; #define LAS __attribute__((address_space(3)))
; __device__ __forceinline__ void tr_item(const float* W, int N, bf16* WT, int ldk, int k0, int scol0, int drow0, LAS float* scr, int lane) {
;     if (scol0 >= 0) {
; #pragma unroll 8
;         for (int i = 0; i < 32; ++i) { const int kk = 2 * i + (lane >> 5); scr[kk * 33 + (lane & 31)] = W[(size_t)(k0 + kk) * N + scol0 + (lane & 31)]; }
;     } else {
; #pragma unroll 8
;         for (int i = 0; i < 32; ++i) { const int kk = 2 * i + (lane >> 5); scr[kk * 33 + (lane & 31)] = 0.f; }
;     }
;     asm volatile("s_waitcnt vmcnt(0) lgkmcnt(0)" ::: "memory");
.LBB0_1186:
	v_add_u32_e32 v46, 0, v28
	v_mad_i64_i32 v[46:47], s[20:21], v46, s69, v[26:27]
	global_load_dword v112, v[46:47], off
	v_add_u32_e32 v48, 2, v17
	v_mad_i64_i32 v[48:49], s[20:21], v48, s69, v[26:27]
	global_load_dword v113, v[48:49], off
	v_add_u32_e32 v46, 0, v30
	v_mad_i64_i32 v[46:47], s[20:21], v46, s69, v[26:27]
	global_load_dword v114, v[46:47], off
	v_add_u32_e32 v48, 2, v19
	v_mad_i64_i32 v[48:49], s[20:21], v48, s69, v[26:27]
	global_load_dword v115, v[48:49], off
	v_add_u32_e32 v46, 0, v32
	v_mad_i64_i32 v[46:47], s[20:21], v46, s69, v[26:27]
	global_load_dword v116, v[46:47], off
	v_add_u32_e32 v48, 2, v21
	v_mad_i64_i32 v[48:49], s[20:21], v48, s69, v[26:27]
	global_load_dword v117, v[48:49], off
	v_add_u32_e32 v46, 0, v34
	v_mad_i64_i32 v[46:47], s[20:21], v46, s69, v[26:27]
	global_load_dword v118, v[46:47], off
	v_add_u32_e32 v48, 2, v29
	v_mad_i64_i32 v[48:49], s[20:21], v48, s69, v[26:27]
	global_load_dword v119, v[48:49], off
	v_add_u32_e32 v46, 0, v36
	v_mad_i64_i32 v[46:47], s[20:21], v46, s69, v[26:27]
	global_load_dword v120, v[46:47], off
	v_add_u32_e32 v48, 2, v31
	v_mad_i64_i32 v[48:49], s[20:21], v48, s69, v[26:27]
	global_load_dword v121, v[48:49], off
	v_add_u32_e32 v46, 0, v38
	v_mad_i64_i32 v[46:47], s[20:21], v46, s69, v[26:27]
	global_load_dword v122, v[46:47], off
	v_add_u32_e32 v48, 2, v33
	v_mad_i64_i32 v[48:49], s[20:21], v48, s69, v[26:27]
	global_load_dword v123, v[48:49], off
	v_add_u32_e32 v46, 0, v40
	v_mad_i64_i32 v[46:47], s[20:21], v46, s69, v[26:27]
	global_load_dword v124, v[46:47], off
	v_add_u32_e32 v48, 2, v35
	v_mad_i64_i32 v[48:49], s[20:21], v48, s69, v[26:27]
	global_load_dword v125, v[48:49], off
	v_add_u32_e32 v46, 0, v42
	v_mad_i64_i32 v[46:47], s[18:19], v46, s69, v[26:27]
	global_load_dword v126, v[46:47], off
	v_add_u32_e32 v48, 2, v37
	v_mad_i64_i32 v[48:49], s[18:19], v48, s69, v[26:27]
	global_load_dword v127, v[48:49], off
	v_add_u32_e32 v46, 32, v28
	v_mad_i64_i32 v[46:47], s[20:21], v46, s69, v[26:27]
	global_load_dword v128, v[46:47], off
	v_add_u32_e32 v48, 34, v17
	v_mad_i64_i32 v[48:49], s[20:21], v48, s69, v[26:27]
	global_load_dword v129, v[48:49], off
	v_add_u32_e32 v46, 32, v30
	v_mad_i64_i32 v[46:47], s[20:21], v46, s69, v[26:27]
	global_load_dword v130, v[46:47], off
	v_add_u32_e32 v48, 34, v19
	v_mad_i64_i32 v[48:49], s[20:21], v48, s69, v[26:27]
	global_load_dword v131, v[48:49], off
	v_add_u32_e32 v46, 32, v32
	v_mad_i64_i32 v[46:47], s[20:21], v46, s69, v[26:27]
	global_load_dword v132, v[46:47], off
	v_add_u32_e32 v48, 34, v21
	v_mad_i64_i32 v[48:49], s[20:21], v48, s69, v[26:27]
	global_load_dword v133, v[48:49], off
	v_add_u32_e32 v46, 32, v34
	v_mad_i64_i32 v[46:47], s[20:21], v46, s69, v[26:27]
	global_load_dword v134, v[46:47], off
	v_add_u32_e32 v48, 34, v29
	v_mad_i64_i32 v[48:49], s[20:21], v48, s69, v[26:27]
	global_load_dword v135, v[48:49], off
	v_add_u32_e32 v46, 32, v36
	v_mad_i64_i32 v[46:47], s[20:21], v46, s69, v[26:27]
	global_load_dword v136, v[46:47], off
	v_add_u32_e32 v48, 34, v31
	v_mad_i64_i32 v[48:49], s[20:21], v48, s69, v[26:27]
	global_load_dword v137, v[48:49], off
	v_add_u32_e32 v46, 32, v38
	v_mad_i64_i32 v[46:47], s[20:21], v46, s69, v[26:27]
	global_load_dword v138, v[46:47], off
	v_add_u32_e32 v48, 34, v33
	v_mad_i64_i32 v[48:49], s[20:21], v48, s69, v[26:27]
	global_load_dword v139, v[48:49], off
	v_add_u32_e32 v46, 32, v40
	v_mad_i64_i32 v[46:47], s[20:21], v46, s69, v[26:27]
	global_load_dword v140, v[46:47], off
	v_add_u32_e32 v48, 34, v35
	v_mad_i64_i32 v[48:49], s[20:21], v48, s69, v[26:27]
	global_load_dword v141, v[48:49], off
	v_add_u32_e32 v46, 32, v42
	v_mad_i64_i32 v[46:47], s[18:19], v46, s69, v[26:27]
	global_load_dword v142, v[46:47], off
	v_add_u32_e32 v48, 34, v37
	v_mad_i64_i32 v[48:49], s[18:19], v48, s69, v[26:27]
	global_load_dword v143, v[48:49], off
	v_add_u32_e32 v50, 0, v4
	v_mad_u64_u32 v[46:47], s[20:21], v50, s57, v[18:19]
	s_waitcnt vmcnt(30)
; #define LAS __attribute__((address_space(3)))
; __device__ __forceinline__ void tr_item(const float* W, int N, bf16* WT, int ldk, int k0, int scol0, int drow0, LAS float* scr, int lane) {
;     if (scol0 >= 0) {
; #pragma unroll 8
;         for (int i = 0; i < 32; ++i) { const int kk = 2 * i + (lane >> 5); scr[kk * 33 + (lane & 31)] = W[(size_t)(k0 + kk) * N + scol0 + (lane & 31)]; }
;     } else {
; #pragma unroll 8
;         for (int i = 0; i < 32; ++i) { const int kk = 2 * i + (lane >> 5); scr[kk * 33 + (lane & 31)] = 0.f; }
;     }
;     asm volatile("s_waitcnt vmcnt(0) lgkmcnt(0)" ::: "memory");
	ds_write_b32 v46, v112
	v_add_u32_e32 v45, 2, v1
	v_mad_u64_u32 v[48:49], s[20:21], v45, s57, v[18:19]
	ds_write_b32 v48, v113
	v_add_u32_e32 v50, 0, v0
	v_mad_u64_u32 v[46:47], s[20:21], v50, s57, v[18:19]
	s_waitcnt vmcnt(28)
	ds_write_b32 v46, v114
	v_add_u32_e32 v45, 2, v3
	v_mad_u64_u32 v[48:49], s[20:21], v45, s57, v[18:19]
	ds_write_b32 v48, v115
	v_add_u32_e32 v50, 0, v6
	v_mad_u64_u32 v[46:47], s[20:21], v50, s57, v[18:19]
	s_waitcnt vmcnt(26)
	ds_write_b32 v46, v116
	v_add_u32_e32 v45, 2, v5
	v_mad_u64_u32 v[48:49], s[20:21], v45, s57, v[18:19]
	ds_write_b32 v48, v117
	v_add_u32_e32 v50, 0, v8
	v_mad_u64_u32 v[46:47], s[20:21], v50, s57, v[18:19]
	s_waitcnt vmcnt(24)
	ds_write_b32 v46, v118
	v_add_u32_e32 v45, 2, v7
	v_mad_u64_u32 v[48:49], s[20:21], v45, s57, v[18:19]
	ds_write_b32 v48, v119
	v_add_u32_e32 v50, 0, v10
	v_mad_u64_u32 v[46:47], s[20:21], v50, s57, v[18:19]
	s_waitcnt vmcnt(22)
	ds_write_b32 v46, v120
	v_add_u32_e32 v45, 2, v9
	v_mad_u64_u32 v[48:49], s[20:21], v45, s57, v[18:19]
	ds_write_b32 v48, v121
	v_add_u32_e32 v50, 0, v12
	v_mad_u64_u32 v[46:47], s[20:21], v50, s57, v[18:19]
	s_waitcnt vmcnt(20)
	ds_write_b32 v46, v122
	v_add_u32_e32 v45, 2, v11
	v_mad_u64_u32 v[48:49], s[20:21], v45, s57, v[18:19]
	ds_write_b32 v48, v123
	v_add_u32_e32 v50, 0, v14
	v_mad_u64_u32 v[46:47], s[20:21], v50, s57, v[18:19]
	s_waitcnt vmcnt(18)
	ds_write_b32 v46, v124
	v_add_u32_e32 v45, 2, v13
	v_mad_u64_u32 v[48:49], s[20:21], v45, s57, v[18:19]
	ds_write_b32 v48, v125
	v_add_u32_e32 v50, 0, v16
	v_mad_u64_u32 v[46:47], s[18:19], v50, s57, v[18:19]
	s_waitcnt vmcnt(16)
	ds_write_b32 v46, v126
	v_add_u32_e32 v45, 2, v15
	v_mad_u64_u32 v[48:49], s[18:19], v45, s57, v[18:19]
	ds_write_b32 v48, v127
	v_add_u32_e32 v50, 32, v4
	v_mad_u64_u32 v[46:47], s[20:21], v50, s57, v[18:19]
	s_waitcnt vmcnt(14)
	ds_write_b32 v46, v128
	v_add_u32_e32 v45, 34, v1
	v_mad_u64_u32 v[48:49], s[20:21], v45, s57, v[18:19]
	ds_write_b32 v48, v129
	v_add_u32_e32 v50, 32, v0
	v_mad_u64_u32 v[46:47], s[20:21], v50, s57, v[18:19]
	s_waitcnt vmcnt(12)
	ds_write_b32 v46, v130
	v_add_u32_e32 v45, 34, v3
	v_mad_u64_u32 v[48:49], s[20:21], v45, s57, v[18:19]
	ds_write_b32 v48, v131
	v_add_u32_e32 v50, 32, v6
	v_mad_u64_u32 v[46:47], s[20:21], v50, s57, v[18:19]
	s_waitcnt vmcnt(10)
	ds_write_b32 v46, v132
	v_add_u32_e32 v45, 34, v5
	v_mad_u64_u32 v[48:49], s[20:21], v45, s57, v[18:19]
	ds_write_b32 v48, v133
	v_add_u32_e32 v50, 32, v8
	v_mad_u64_u32 v[46:47], s[20:21], v50, s57, v[18:19]
	s_waitcnt vmcnt(8)
	ds_write_b32 v46, v134
	v_add_u32_e32 v45, 34, v7
	v_mad_u64_u32 v[48:49], s[20:21], v45, s57, v[18:19]
	ds_write_b32 v48, v135
	v_add_u32_e32 v50, 32, v10
	v_mad_u64_u32 v[46:47], s[20:21], v50, s57, v[18:19]
	s_waitcnt vmcnt(6)
	ds_write_b32 v46, v136
	v_add_u32_e32 v45, 34, v9
	v_mad_u64_u32 v[48:49], s[20:21], v45, s57, v[18:19]
	ds_write_b32 v48, v137
	v_add_u32_e32 v50, 32, v12
	v_mad_u64_u32 v[46:47], s[20:21], v50, s57, v[18:19]
	s_waitcnt vmcnt(4)
	ds_write_b32 v46, v138
	v_add_u32_e32 v45, 34, v11
	v_mad_u64_u32 v[48:49], s[20:21], v45, s57, v[18:19]
	ds_write_b32 v48, v139
	v_add_u32_e32 v50, 32, v14
	v_mad_u64_u32 v[46:47], s[20:21], v50, s57, v[18:19]
	s_waitcnt vmcnt(2)
	ds_write_b32 v46, v140
	v_add_u32_e32 v45, 34, v13
	v_mad_u64_u32 v[48:49], s[20:21], v45, s57, v[18:19]
	ds_write_b32 v48, v141
	v_add_u32_e32 v50, 32, v16
	v_mad_u64_u32 v[46:47], s[18:19], v50, s57, v[18:19]
	s_waitcnt vmcnt(0)
	ds_write_b32 v46, v142
	v_add_u32_e32 v45, 34, v15
	v_mad_u64_u32 v[48:49], s[18:19], v45, s57, v[18:19]
	ds_write_b32 v48, v143
	s_mov_b32 s12, 32
	s_mov_b32 s5, 33
	s_mov_b32 s17, 32
	s_mov_b32 s18, 34
	s_mov_b32 s13, 0
	s_cmp_eq_u32 s13, 0
	s_branch .LBB0_1179

; #define LAS __attribute__((address_space(3)))
; __device__ __forceinline__ void tr_item(const float* W, int N, bf16* WT, int ldk, int k0, int scol0, int drow0, LAS float* scr, int lane) {
;     if (scol0 >= 0) {
; #pragma unroll 8
;         for (int i = 0; i < 32; ++i) { const int kk = 2 * i + (lane >> 5); scr[kk * 33 + (lane & 31)] = W[(size_t)(k0 + kk) * N + scol0 + (lane & 31)]; }
;     } else {
; #pragma unroll 8
;         for (int i = 0; i < 32; ++i) { const int kk = 2 * i + (lane >> 5); scr[kk * 33 + (lane & 31)] = 0.f; }
;     }
;     asm volatile("s_waitcnt vmcnt(0) lgkmcnt(0)" ::: "memory");
.LBB0_1196:
	v_add_u32_e32 v44, 0, v26
	v_ashrrev_i32_e32 v45, 31, v44
	v_lshlrev_b64 v[44:45], 13, v[44:45]
	v_lshl_add_u64 v[44:45], v[24:25], 0, v[44:45]
	global_load_dword v112, v[44:45], off
	v_add_u32_e32 v42, 2, v17
	v_ashrrev_i32_e32 v43, 31, v42
	v_lshlrev_b64 v[42:43], 13, v[42:43]
	v_lshl_add_u64 v[42:43], v[24:25], 0, v[42:43]
	global_load_dword v113, v[42:43], off
	v_add_u32_e32 v44, 0, v28
	v_ashrrev_i32_e32 v45, 31, v44
	v_lshlrev_b64 v[44:45], 13, v[44:45]
	v_lshl_add_u64 v[44:45], v[24:25], 0, v[44:45]
	global_load_dword v114, v[44:45], off
	v_add_u32_e32 v42, 2, v19
	v_ashrrev_i32_e32 v43, 31, v42
	v_lshlrev_b64 v[42:43], 13, v[42:43]
	v_lshl_add_u64 v[42:43], v[24:25], 0, v[42:43]
	global_load_dword v115, v[42:43], off
	v_add_u32_e32 v44, 0, v30
	v_ashrrev_i32_e32 v45, 31, v44
	v_lshlrev_b64 v[44:45], 13, v[44:45]
	v_lshl_add_u64 v[44:45], v[24:25], 0, v[44:45]
	global_load_dword v116, v[44:45], off
	v_add_u32_e32 v42, 2, v27
	v_ashrrev_i32_e32 v43, 31, v42
	v_lshlrev_b64 v[42:43], 13, v[42:43]
	v_lshl_add_u64 v[42:43], v[24:25], 0, v[42:43]
	global_load_dword v117, v[42:43], off
	v_add_u32_e32 v44, 0, v32
	v_ashrrev_i32_e32 v45, 31, v44
	v_lshlrev_b64 v[44:45], 13, v[44:45]
	v_lshl_add_u64 v[44:45], v[24:25], 0, v[44:45]
	global_load_dword v118, v[44:45], off
	v_add_u32_e32 v42, 2, v29
	v_ashrrev_i32_e32 v43, 31, v42
	v_lshlrev_b64 v[42:43], 13, v[42:43]
	v_lshl_add_u64 v[42:43], v[24:25], 0, v[42:43]
	global_load_dword v119, v[42:43], off
	v_add_u32_e32 v44, 0, v34
	v_ashrrev_i32_e32 v45, 31, v44
	v_lshlrev_b64 v[44:45], 13, v[44:45]
	v_lshl_add_u64 v[44:45], v[24:25], 0, v[44:45]
	global_load_dword v120, v[44:45], off
	v_add_u32_e32 v42, 2, v31
	v_ashrrev_i32_e32 v43, 31, v42
	v_lshlrev_b64 v[42:43], 13, v[42:43]
	v_lshl_add_u64 v[42:43], v[24:25], 0, v[42:43]
	global_load_dword v121, v[42:43], off
	v_add_u32_e32 v44, 0, v36
	v_ashrrev_i32_e32 v45, 31, v44
	v_lshlrev_b64 v[44:45], 13, v[44:45]
	v_lshl_add_u64 v[44:45], v[24:25], 0, v[44:45]
	global_load_dword v122, v[44:45], off
	v_add_u32_e32 v42, 2, v33
	v_ashrrev_i32_e32 v43, 31, v42
	v_lshlrev_b64 v[42:43], 13, v[42:43]
	v_lshl_add_u64 v[42:43], v[24:25], 0, v[42:43]
	global_load_dword v123, v[42:43], off
	v_add_u32_e32 v44, 0, v38
	v_ashrrev_i32_e32 v45, 31, v44
	v_lshlrev_b64 v[44:45], 13, v[44:45]
	v_lshl_add_u64 v[44:45], v[24:25], 0, v[44:45]
	global_load_dword v124, v[44:45], off
	v_add_u32_e32 v42, 2, v35
	v_ashrrev_i32_e32 v43, 31, v42
	v_lshlrev_b64 v[42:43], 13, v[42:43]
	v_lshl_add_u64 v[42:43], v[24:25], 0, v[42:43]
	global_load_dword v125, v[42:43], off
	v_add_u32_e32 v44, 0, v40
	v_ashrrev_i32_e32 v45, 31, v44
	v_lshlrev_b64 v[44:45], 13, v[44:45]
	v_lshl_add_u64 v[44:45], v[24:25], 0, v[44:45]
	global_load_dword v126, v[44:45], off
	v_add_u32_e32 v42, 2, v37
	v_ashrrev_i32_e32 v43, 31, v42
	v_lshlrev_b64 v[42:43], 13, v[42:43]
	v_lshl_add_u64 v[42:43], v[24:25], 0, v[42:43]
	global_load_dword v127, v[42:43], off
	v_add_u32_e32 v44, 32, v26
	v_ashrrev_i32_e32 v45, 31, v44
	v_lshlrev_b64 v[44:45], 13, v[44:45]
	v_lshl_add_u64 v[44:45], v[24:25], 0, v[44:45]
	global_load_dword v128, v[44:45], off
	v_add_u32_e32 v42, 34, v17
	v_ashrrev_i32_e32 v43, 31, v42
	v_lshlrev_b64 v[42:43], 13, v[42:43]
	v_lshl_add_u64 v[42:43], v[24:25], 0, v[42:43]
	global_load_dword v129, v[42:43], off
	v_add_u32_e32 v44, 32, v28
	v_ashrrev_i32_e32 v45, 31, v44
	v_lshlrev_b64 v[44:45], 13, v[44:45]
	v_lshl_add_u64 v[44:45], v[24:25], 0, v[44:45]
	global_load_dword v130, v[44:45], off
	v_add_u32_e32 v42, 34, v19
	v_ashrrev_i32_e32 v43, 31, v42
	v_lshlrev_b64 v[42:43], 13, v[42:43]
	v_lshl_add_u64 v[42:43], v[24:25], 0, v[42:43]
	global_load_dword v131, v[42:43], off
	v_add_u32_e32 v44, 32, v30
	v_ashrrev_i32_e32 v45, 31, v44
	v_lshlrev_b64 v[44:45], 13, v[44:45]
	v_lshl_add_u64 v[44:45], v[24:25], 0, v[44:45]
	global_load_dword v132, v[44:45], off
	v_add_u32_e32 v42, 34, v27
	v_ashrrev_i32_e32 v43, 31, v42
	v_lshlrev_b64 v[42:43], 13, v[42:43]
	v_lshl_add_u64 v[42:43], v[24:25], 0, v[42:43]
	global_load_dword v133, v[42:43], off
	v_add_u32_e32 v44, 32, v32
	v_ashrrev_i32_e32 v45, 31, v44
	v_lshlrev_b64 v[44:45], 13, v[44:45]
	v_lshl_add_u64 v[44:45], v[24:25], 0, v[44:45]
	global_load_dword v134, v[44:45], off
	v_add_u32_e32 v42, 34, v29
	v_ashrrev_i32_e32 v43, 31, v42
	v_lshlrev_b64 v[42:43], 13, v[42:43]
	v_lshl_add_u64 v[42:43], v[24:25], 0, v[42:43]
	global_load_dword v135, v[42:43], off
	v_add_u32_e32 v44, 32, v34
	v_ashrrev_i32_e32 v45, 31, v44
	v_lshlrev_b64 v[44:45], 13, v[44:45]
	v_lshl_add_u64 v[44:45], v[24:25], 0, v[44:45]
	global_load_dword v136, v[44:45], off
	v_add_u32_e32 v42, 34, v31
	v_ashrrev_i32_e32 v43, 31, v42
	v_lshlrev_b64 v[42:43], 13, v[42:43]
	v_lshl_add_u64 v[42:43], v[24:25], 0, v[42:43]
	global_load_dword v137, v[42:43], off
	v_add_u32_e32 v44, 32, v36
	v_ashrrev_i32_e32 v45, 31, v44
	v_lshlrev_b64 v[44:45], 13, v[44:45]
	v_lshl_add_u64 v[44:45], v[24:25], 0, v[44:45]
	global_load_dword v138, v[44:45], off
	v_add_u32_e32 v42, 34, v33
	v_ashrrev_i32_e32 v43, 31, v42
	v_lshlrev_b64 v[42:43], 13, v[42:43]
	v_lshl_add_u64 v[42:43], v[24:25], 0, v[42:43]
	global_load_dword v139, v[42:43], off
	v_add_u32_e32 v44, 32, v38
	v_ashrrev_i32_e32 v45, 31, v44
	v_lshlrev_b64 v[44:45], 13, v[44:45]
	v_lshl_add_u64 v[44:45], v[24:25], 0, v[44:45]
	global_load_dword v140, v[44:45], off
	v_add_u32_e32 v42, 34, v35
	v_ashrrev_i32_e32 v43, 31, v42
	v_lshlrev_b64 v[42:43], 13, v[42:43]
	v_lshl_add_u64 v[42:43], v[24:25], 0, v[42:43]
	global_load_dword v141, v[42:43], off
	v_add_u32_e32 v44, 32, v40
	v_ashrrev_i32_e32 v45, 31, v44
	v_lshlrev_b64 v[44:45], 13, v[44:45]
	v_lshl_add_u64 v[44:45], v[24:25], 0, v[44:45]
	global_load_dword v142, v[44:45], off
	v_add_u32_e32 v42, 34, v37
	v_ashrrev_i32_e32 v43, 31, v42
	v_lshlrev_b64 v[42:43], 13, v[42:43]
	v_lshl_add_u64 v[42:43], v[24:25], 0, v[42:43]
	global_load_dword v143, v[42:43], off
	v_add_u32_e32 v47, 0, v4
	v_mad_u64_u32 v[42:43], s[8:9], v47, s57, v[18:19]
	s_waitcnt vmcnt(30)
; #define LAS __attribute__((address_space(3)))
; __device__ __forceinline__ void tr_item(const float* W, int N, bf16* WT, int ldk, int k0, int scol0, int drow0, LAS float* scr, int lane) {
;     if (scol0 >= 0) {
; #pragma unroll 8
;         for (int i = 0; i < 32; ++i) { const int kk = 2 * i + (lane >> 5); scr[kk * 33 + (lane & 31)] = W[(size_t)(k0 + kk) * N + scol0 + (lane & 31)]; }
;     } else {
; #pragma unroll 8
;         for (int i = 0; i < 32; ++i) { const int kk = 2 * i + (lane >> 5); scr[kk * 33 + (lane & 31)] = 0.f; }
;     }
;     asm volatile("s_waitcnt vmcnt(0) lgkmcnt(0)" ::: "memory");
	ds_write_b32 v42, v112
	v_add_u32_e32 v46, 2, v1
	v_mad_u64_u32 v[44:45], s[8:9], v46, s57, v[18:19]
	ds_write_b32 v44, v113
	v_add_u32_e32 v47, 0, v0
	v_mad_u64_u32 v[42:43], s[8:9], v47, s57, v[18:19]
	s_waitcnt vmcnt(28)
	ds_write_b32 v42, v114
	v_add_u32_e32 v46, 2, v3
	v_mad_u64_u32 v[44:45], s[8:9], v46, s57, v[18:19]
	ds_write_b32 v44, v115
	v_add_u32_e32 v47, 0, v6
	v_mad_u64_u32 v[42:43], s[8:9], v47, s57, v[18:19]
	s_waitcnt vmcnt(26)
	ds_write_b32 v42, v116
	v_add_u32_e32 v46, 2, v5
	v_mad_u64_u32 v[44:45], s[8:9], v46, s57, v[18:19]
	ds_write_b32 v44, v117
	v_add_u32_e32 v47, 0, v8
	v_mad_u64_u32 v[42:43], s[8:9], v47, s57, v[18:19]
	s_waitcnt vmcnt(24)
	ds_write_b32 v42, v118
	v_add_u32_e32 v46, 2, v7
	v_mad_u64_u32 v[44:45], s[8:9], v46, s57, v[18:19]
	ds_write_b32 v44, v119
	v_add_u32_e32 v47, 0, v10
	v_mad_u64_u32 v[42:43], s[8:9], v47, s57, v[18:19]
	s_waitcnt vmcnt(22)
	ds_write_b32 v42, v120
	v_add_u32_e32 v46, 2, v9
	v_mad_u64_u32 v[44:45], s[8:9], v46, s57, v[18:19]
	ds_write_b32 v44, v121
	v_add_u32_e32 v47, 0, v12
	v_mad_u64_u32 v[42:43], s[8:9], v47, s57, v[18:19]
	s_waitcnt vmcnt(20)
	ds_write_b32 v42, v122
	v_add_u32_e32 v46, 2, v11
	v_mad_u64_u32 v[44:45], s[8:9], v46, s57, v[18:19]
	ds_write_b32 v44, v123
	v_add_u32_e32 v47, 0, v14
	v_mad_u64_u32 v[42:43], s[8:9], v47, s57, v[18:19]
	s_waitcnt vmcnt(18)
	ds_write_b32 v42, v124
	v_add_u32_e32 v46, 2, v13
	v_mad_u64_u32 v[44:45], s[8:9], v46, s57, v[18:19]
	ds_write_b32 v44, v125
	v_add_u32_e32 v47, 0, v16
	v_mad_u64_u32 v[42:43], s[6:7], v47, s57, v[18:19]
	s_waitcnt vmcnt(16)
	ds_write_b32 v42, v126
	v_add_u32_e32 v46, 2, v15
	v_mad_u64_u32 v[44:45], s[6:7], v46, s57, v[18:19]
	ds_write_b32 v44, v127
	v_add_u32_e32 v47, 32, v4
	v_mad_u64_u32 v[42:43], s[8:9], v47, s57, v[18:19]
	s_waitcnt vmcnt(14)
	ds_write_b32 v42, v128
	v_add_u32_e32 v46, 34, v1
	v_mad_u64_u32 v[44:45], s[8:9], v46, s57, v[18:19]
	ds_write_b32 v44, v129
	v_add_u32_e32 v47, 32, v0
	v_mad_u64_u32 v[42:43], s[8:9], v47, s57, v[18:19]
	s_waitcnt vmcnt(12)
	ds_write_b32 v42, v130
	v_add_u32_e32 v46, 34, v3
	v_mad_u64_u32 v[44:45], s[8:9], v46, s57, v[18:19]
	ds_write_b32 v44, v131
	v_add_u32_e32 v47, 32, v6
	v_mad_u64_u32 v[42:43], s[8:9], v47, s57, v[18:19]
	s_waitcnt vmcnt(10)
	ds_write_b32 v42, v132
	v_add_u32_e32 v46, 34, v5
	v_mad_u64_u32 v[44:45], s[8:9], v46, s57, v[18:19]
	ds_write_b32 v44, v133
	v_add_u32_e32 v47, 32, v8
	v_mad_u64_u32 v[42:43], s[8:9], v47, s57, v[18:19]
	s_waitcnt vmcnt(8)
	ds_write_b32 v42, v134
	v_add_u32_e32 v46, 34, v7
	v_mad_u64_u32 v[44:45], s[8:9], v46, s57, v[18:19]
	ds_write_b32 v44, v135
	v_add_u32_e32 v47, 32, v10
	v_mad_u64_u32 v[42:43], s[8:9], v47, s57, v[18:19]
	s_waitcnt vmcnt(6)
	ds_write_b32 v42, v136
	v_add_u32_e32 v46, 34, v9
	v_mad_u64_u32 v[44:45], s[8:9], v46, s57, v[18:19]
	ds_write_b32 v44, v137
	v_add_u32_e32 v47, 32, v12
	v_mad_u64_u32 v[42:43], s[8:9], v47, s57, v[18:19]
	s_waitcnt vmcnt(4)
	ds_write_b32 v42, v138
	v_add_u32_e32 v46, 34, v11
	v_mad_u64_u32 v[44:45], s[8:9], v46, s57, v[18:19]
	ds_write_b32 v44, v139
	v_add_u32_e32 v47, 32, v14
	v_mad_u64_u32 v[42:43], s[8:9], v47, s57, v[18:19]
	s_waitcnt vmcnt(2)
	ds_write_b32 v42, v140
	v_add_u32_e32 v46, 34, v13
	v_mad_u64_u32 v[44:45], s[8:9], v46, s57, v[18:19]
	ds_write_b32 v44, v141
	v_add_u32_e32 v47, 32, v16
	v_mad_u64_u32 v[42:43], s[6:7], v47, s57, v[18:19]
	s_waitcnt vmcnt(0)
	ds_write_b32 v42, v142
	v_add_u32_e32 v46, 34, v15
	v_mad_u64_u32 v[44:45], s[6:7], v46, s57, v[18:19]
	ds_write_b32 v44, v143
	s_mov_b32 s4, 32
	s_mov_b32 s3, 33
	s_mov_b32 s6, 32
	s_mov_b32 s7, 34
	s_mov_b32 s5, 0
	s_cmp_eq_u32 s5, 0
	s_branch .LBB0_1189
